# attn_d: K/V global prefetch two tiles ahead (second staging register set borrowed from hoisted constants, counted vmcnt(4) before the LDS writes)
# baseline (speedup 1.0000x reference)
.LBB0_610:
	s_ashr_i32 s5, s23, 7
	s_bfe_u32 s4, s23, 0x20005
	s_mul_hi_i32 s8, s5, 0x3e00000
	s_mul_i32 s5, s5, 0x3e00000
	s_add_u32 s18, s2, s5
	s_addc_u32 s19, s17, s8
	s_lshl_b32 s5, s23, 7
	s_and_b32 s5, s5, 0xf80
	v_and_b32_e32 v64, 15, v2
	v_lshl_add_u32 v0, v3, 4, s5
	v_or_b32_e32 v66, v0, v64
	v_mov_b64_e32 v[20:21], s[18:19]
	v_mad_i64_i32 v[4:5], s[18:19], v66, s65, v[20:21]
	s_lshl_b32 s8, s4, 8
	v_bfe_u32 v65, v2, 4, 2
	v_lshl_add_u64 v[4:5], v[4:5], 0, s[8:9]
	s_mov_b64 s[18:19], 0x2200
	v_lshl_add_u64 v[132:133], v[4:5], 0, s[18:19]
	v_lshlrev_b32_e32 v0, 4, v65
	v_lshl_add_u64 v[16:17], v[132:133], 0, v[0:1]
	v_ashrrev_i32_e32 v67, 4, v2
	global_load_dwordx4 v[4:7], v[16:17], off
	global_load_dwordx4 v[8:11], v[16:17], off offset:64
	global_load_dwordx4 v[12:15], v[16:17], off offset:128
	s_nop 0
	global_load_dwordx4 v[16:19], v[16:17], off offset:192
	v_lshlrev_b32_e32 v0, 4, v2
	v_mad_i64_i32 v[20:21], s[18:19], v67, s65, v[20:21]
	v_lshl_add_u64 v[20:21], v[20:21], 0, s[8:9]
	v_and_b32_e32 v0, 0xf0, v0
	v_lshl_add_u64 v[36:37], v[20:21], 0, v[0:1]
	v_add_co_u32_e32 v24, vcc, s64, v36
	s_mov_b32 s5, 0x7e000
	s_nop 0
	v_addc_co_u32_e32 v25, vcc, 0, v37, vcc
	v_add_co_u32_e32 v32, vcc, s5, v36
	s_mov_b64 s[18:19], 0x2600
	s_waitcnt lgkmcnt(0)
	v_addc_co_u32_e32 v33, vcc, 0, v37, vcc
	global_load_dwordx4 v[20:23], v[24:25], off offset:1536
	s_nop 0
	global_load_dwordx4 v[24:27], v[24:25], off offset:2560
	s_nop 0
	global_load_dwordx4 v[28:31], v[32:33], off offset:1536
	s_nop 0
	global_load_dwordx4 v[32:35], v[32:33], off offset:2560
	v_lshl_add_u64 v[134:135], v[36:37], 0, s[18:19]
	s_mov_b64 s[18:19], 0x2a00
	v_lshl_add_u64 v[136:137], v[36:37], 0, s[18:19]
	v_mul_lo_u32 v36, v67, s21
	v_add3_u32 v169, 0, v0, v36
	v_lshlrev_b32_e32 v167, 2, v65
	s_barrier
	s_not_b32 s4, s4
	s_lshl_b32 s4, s4, 1
	v_ldexp_f32 v0, 1.0, s4
	v_lshlrev_b32_e32 v68, 3, v65
	v_mul_f32_e32 v150, 0x3fb8aa3b, v0
	v_readfirstlane_b32 s4, v3
	v_mul_u32_u24_e32 v0, 0x90, v64
	s_cmp_gt_i32 s4, 3
	s_mov_b64 s[4:5], -1
	v_lshlrev_b32_e32 v171, 1, v0
	v_lshlrev_b32_e32 v172, 1, v68
	s_waitcnt vmcnt(3)
	ds_write_b128 v169, v[20:23]
	s_waitcnt vmcnt(2)
	ds_write_b128 v169, v[24:27] offset:36864
	s_waitcnt vmcnt(1)
	ds_write_b128 v169, v[28:31] offset:9216
	s_waitcnt vmcnt(0)
	ds_write_b128 v169, v[32:35] offset:46080
	v_lshlrev_b32_e32 v38, 16, v4
	v_and_b32_e32 v39, 0xffff0000, v4
	v_lshlrev_b32_e32 v4, 16, v5
	v_and_b32_e32 v5, 0xffff0000, v5
	v_lshlrev_b32_e32 v50, 16, v16
	v_and_b32_e32 v51, 0xffff0000, v16
	v_pk_mul_f32 v[38:39], v[38:39], s[16:17] op_sel_hi:[1,0]
	v_pk_mul_f32 v[52:53], v[4:5], s[16:17] op_sel_hi:[1,0]
	v_cvt_pk_bf16_f32 v4, v38, v39
	v_pk_mul_f32 v[38:39], v[50:51], s[16:17] op_sel_hi:[1,0]
	v_sub_u32_e32 v20, v167, v66
	v_cvt_pk_bf16_f32 v16, v38, v39
	v_lshlrev_b32_e32 v38, 16, v17
	v_and_b32_e32 v39, 0xffff0000, v17
	v_pk_mul_f32 v[38:39], v[38:39], s[16:17] op_sel_hi:[1,0]
	v_cvt_f32_i32_e32 v170, v20
	v_cvt_pk_bf16_f32 v17, v38, v39
	v_lshlrev_b32_e32 v38, 16, v18
	v_and_b32_e32 v39, 0xffff0000, v18
	v_pk_mul_f32 v[38:39], v[38:39], s[16:17] op_sel_hi:[1,0]
	v_lshlrev_b32_e32 v40, 16, v6
	v_cvt_pk_bf16_f32 v18, v38, v39
	v_lshlrev_b32_e32 v38, 16, v19
	v_and_b32_e32 v39, 0xffff0000, v19
	v_pk_mul_f32 v[38:39], v[38:39], s[16:17] op_sel_hi:[1,0]
	v_and_b32_e32 v41, 0xffff0000, v6
	v_cvt_pk_bf16_f32 v19, v38, v39
	v_lshlrev_b32_e32 v38, 3, v2
	v_bfe_u32 v2, v2, 2, 2
	v_lshlrev_b32_e32 v6, 16, v7
	v_and_b32_e32 v7, 0xffff0000, v7
	v_lshlrev_b32_e32 v42, 16, v8
	v_and_b32_e32 v43, 0xffff0000, v8
	v_lshlrev_b32_e32 v8, 16, v9
	v_and_b32_e32 v9, 0xffff0000, v9
	v_lshlrev_b32_e32 v44, 16, v10
	v_and_b32_e32 v45, 0xffff0000, v10
	v_lshlrev_b32_e32 v10, 16, v11
	v_and_b32_e32 v11, 0xffff0000, v11
	v_lshlrev_b32_e32 v46, 16, v12
	v_and_b32_e32 v47, 0xffff0000, v12
	v_lshlrev_b32_e32 v12, 16, v13
	v_and_b32_e32 v13, 0xffff0000, v13
	v_lshlrev_b32_e32 v48, 16, v14
	v_and_b32_e32 v49, 0xffff0000, v14
	v_lshlrev_b32_e32 v14, 16, v15
	v_and_b32_e32 v15, 0xffff0000, v15
	v_or_b32_e32 v2, v167, v2
	v_pk_mul_f32 v[40:41], v[40:41], s[16:17] op_sel_hi:[1,0]
	v_pk_mul_f32 v[54:55], v[6:7], s[16:17] op_sel_hi:[1,0]
	v_pk_mul_f32 v[42:43], v[42:43], s[16:17] op_sel_hi:[1,0]
	v_pk_mul_f32 v[56:57], v[8:9], s[16:17] op_sel_hi:[1,0]
	v_pk_mul_f32 v[44:45], v[44:45], s[16:17] op_sel_hi:[1,0]
	v_pk_mul_f32 v[58:59], v[10:11], s[16:17] op_sel_hi:[1,0]
	v_pk_mul_f32 v[46:47], v[46:47], s[16:17] op_sel_hi:[1,0]
	v_pk_mul_f32 v[60:61], v[12:13], s[16:17] op_sel_hi:[1,0]
	v_pk_mul_f32 v[48:49], v[48:49], s[16:17] op_sel_hi:[1,0]
	v_pk_mul_f32 v[62:63], v[14:15], s[16:17] op_sel_hi:[1,0]
	v_and_b32_e32 v3, 24, v38
	v_mad_u32_u24 v2, v2, s21, 0
	v_cvt_pk_bf16_f32 v5, v52, v53
	v_cvt_pk_bf16_f32 v6, v40, v41
	v_cvt_pk_bf16_f32 v7, v54, v55
	v_cvt_pk_bf16_f32 v8, v42, v43
	v_cvt_pk_bf16_f32 v9, v56, v57
	v_cvt_pk_bf16_f32 v10, v44, v45
	v_cvt_pk_bf16_f32 v11, v58, v59
	v_cvt_pk_bf16_f32 v12, v46, v47
	v_cvt_pk_bf16_f32 v13, v60, v61
	v_cvt_pk_bf16_f32 v14, v48, v49
	v_cvt_pk_bf16_f32 v15, v62, v63
	v_add_u32_e32 v168, v2, v3
	s_waitcnt lgkmcnt(0)
	s_barrier
	s_cbranch_scc0 .Ld_groupA
	v_mov_b32_e32 v28, 0
	v_mov_b32_e32 v29, 0
	v_mov_b32_e32 v30, 0
	v_mov_b32_e32 v31, 0
	v_mov_b32_e32 v32, 0
	v_mov_b32_e32 v33, 0
	v_mov_b32_e32 v34, 0
	v_mov_b32_e32 v35, 0
	v_mov_b32_e32 v40, 0
	v_mov_b32_e32 v41, 0
	v_mov_b32_e32 v42, 0
	v_mov_b32_e32 v43, 0
	v_mov_b32_e32 v52, 0
	v_mov_b32_e32 v53, 0
	v_mov_b32_e32 v54, 0
	v_mov_b32_e32 v55, 0
	v_mov_b32_e32 v56, 0
	v_mov_b32_e32 v57, 0
	v_mov_b32_e32 v58, 0
	v_mov_b32_e32 v59, 0
	v_mov_b32_e32 v64, 0
	v_mov_b32_e32 v65, 0
	v_mov_b32_e32 v66, 0
	v_mov_b32_e32 v67, 0
	v_mov_b32_e32 v72, 0
	v_mov_b32_e32 v73, 0
	v_mov_b32_e32 v74, 0
	v_mov_b32_e32 v75, 0
	v_mov_b32_e32 v84, 0
	v_mov_b32_e32 v85, 0
	v_mov_b32_e32 v86, 0
	v_mov_b32_e32 v87, 0
	v_mov_b32_e32 v36, 0
	v_mov_b32_e32 v37, 0
	v_mov_b32_e32 v38, 0
	v_mov_b32_e32 v39, 0
	v_mov_b32_e32 v44, 0
	v_mov_b32_e32 v45, 0
	v_mov_b32_e32 v46, 0
	v_mov_b32_e32 v47, 0
	v_mov_b32_e32 v48, 0
	v_mov_b32_e32 v49, 0
	v_mov_b32_e32 v50, 0
	v_mov_b32_e32 v51, 0
	v_mov_b32_e32 v60, 0
	v_mov_b32_e32 v61, 0
	v_mov_b32_e32 v62, 0
	v_mov_b32_e32 v63, 0
	v_mov_b32_e32 v68, 0
	v_mov_b32_e32 v69, 0
	v_mov_b32_e32 v70, 0
	v_mov_b32_e32 v71, 0
	v_mov_b32_e32 v76, 0
	v_mov_b32_e32 v77, 0
	v_mov_b32_e32 v78, 0
	v_mov_b32_e32 v79, 0
	v_mov_b32_e32 v80, 0
	v_mov_b32_e32 v81, 0
	v_mov_b32_e32 v82, 0
	v_mov_b32_e32 v83, 0
	v_mov_b32_e32 v20, 0
	v_mov_b32_e32 v21, 0
	v_mov_b32_e32 v22, 0
	v_mov_b32_e32 v23, 0
	v_mov_b32_e32 v120, 0
	v_mov_b32_e32 v121, 0
	v_mov_b32_e32 v122, 0
	v_mov_b32_e32 v123, 0
	v_mov_b32_e32 v124, 0
	v_mov_b32_e32 v125, 0
	v_mov_b32_e32 v126, 0
	v_mov_b32_e32 v127, 0
	v_mov_b32_e32 v128, 0
	v_mov_b32_e32 v129, 0
	v_mov_b32_e32 v130, 0
	v_mov_b32_e32 v131, 0
	v_mov_b32_e32 v152, 0
	v_mov_b32_e32 v153, 0
	v_mov_b32_e32 v154, 0
	v_mov_b32_e32 v155, 0
	v_mov_b32_e32 v0, 0
	v_mov_b32_e32 v151, 0
	v_mov_b32_e32 v24, 0
	v_mov_b32_e32 v25, 0
	s_mov_b32 s66, 0xff800000
	v_add_u32_e32 v255, v171, v172
	v_mov_b32_e32 v165, v170
	v_readfirstlane_b32 s42, v134
	v_readfirstlane_b32 s43, v135
	v_readfirstlane_b32 s46, v136
	v_readfirstlane_b32 s47, v137
	s_nop 3
	v_subrev_u32_e32 v173, s42, v134
	v_subrev_u32_e32 v175, s46, v136
	s_mov_b32 s5, 0
	s_mov_b32 s31, 0
	s_mov_b32 s38, 0
	s_mov_b32 s39, 0x4800
	s_mov_b32 s30, 0xf8000
	v_add_u32_e32 v174, s31, v168
	v_add_u32_e32 v164, s39, v169
	s_add_u32 s80, s42, s30
	s_addc_u32 s81, s43, 0
	s_add_u32 s86, s80, 0x7c000
	s_addc_u32 s87, s81, 0
	s_add_u32 s96, s46, s30
	s_addc_u32 s97, s47, 0
	s_add_u32 s98, s96, 0x7c000
	s_addc_u32 s99, s97, 0
	global_load_dwordx4 v[138:141], v173, s[80:81]
	global_load_dwordx4 v[146:149], v175, s[96:97]
	global_load_dwordx4 v[142:145], v173, s[86:87]
	global_load_dwordx4 v[194:197], v175, s[98:99]
	s_mov_b32 s30, 0x1f0000
	v_add_u32_e32 v174, s31, v168
	v_add_u32_e32 v164, s39, v169
	s_add_u32 s80, s42, s30
	s_addc_u32 s81, s43, 0
	s_add_u32 s86, s80, 0x7c000
	s_addc_u32 s87, s81, 0
	s_add_u32 s96, s46, s30
	s_addc_u32 s97, s47, 0
	s_add_u32 s98, s96, 0x7c000
	s_addc_u32 s99, s97, 0
	v_mov_b32_e32 v88, 0xff800000
	v_mov_b32_e32 v89, 0xff800000
	v_mov_b32_e32 v90, 0xff800000
	v_mov_b32_e32 v91, 0xff800000
	v_mov_b32_e32 v92, 0xff800000
	v_mov_b32_e32 v93, 0xff800000
	v_mov_b32_e32 v94, 0xff800000
	v_mov_b32_e32 v95, 0xff800000
	v_mov_b32_e32 v96, 0xff800000
	v_mov_b32_e32 v97, 0xff800000
	v_mov_b32_e32 v98, 0xff800000
	v_mov_b32_e32 v99, 0xff800000
	v_mov_b32_e32 v100, 0xff800000
	v_mov_b32_e32 v101, 0xff800000
	v_mov_b32_e32 v102, 0xff800000
	v_mov_b32_e32 v103, 0xff800000
	v_mov_b32_e32 v104, 0xff800000
	v_mov_b32_e32 v105, 0xff800000
	v_mov_b32_e32 v106, 0xff800000
	v_mov_b32_e32 v107, 0xff800000
	v_mov_b32_e32 v108, 0xff800000
	v_mov_b32_e32 v109, 0xff800000
	v_mov_b32_e32 v110, 0xff800000
	v_mov_b32_e32 v111, 0xff800000
	v_mov_b32_e32 v112, 0xff800000
	v_mov_b32_e32 v113, 0xff800000
	v_mov_b32_e32 v114, 0xff800000
	v_mov_b32_e32 v115, 0xff800000
	v_mov_b32_e32 v116, 0xff800000
	v_mov_b32_e32 v117, 0xff800000
	v_mov_b32_e32 v118, 0xff800000
	v_mov_b32_e32 v119, 0xff800000

.Ld_nr_B0_1:
	v_exp_f32_e32 v104, v104
	v_exp_f32_e32 v105, v105
	v_exp_f32_e32 v106, v106
	v_exp_f32_e32 v107, v107
	v_exp_f32_e32 v108, v108
	v_exp_f32_e32 v109, v109
	v_exp_f32_e32 v110, v110
	v_exp_f32_e32 v111, v111
	v_exp_f32_e32 v112, v112
	v_exp_f32_e32 v113, v113
	v_exp_f32_e32 v114, v114
	v_exp_f32_e32 v115, v115
	v_exp_f32_e32 v116, v116
	v_exp_f32_e32 v117, v117
	v_exp_f32_e32 v118, v118
	v_exp_f32_e32 v119, v119
	s_nop 0
	v_add_f32_e32 v26, v104, v105
	v_add_f32_e32 v26, v26, v106
	v_add_f32_e32 v26, v26, v107
	v_add_f32_e32 v26, v26, v108
	v_add_f32_e32 v26, v26, v109
	v_add_f32_e32 v26, v26, v110
	v_add_f32_e32 v26, v26, v111
	v_add_f32_e32 v26, v26, v112
	v_add_f32_e32 v26, v26, v113
	v_add_f32_e32 v26, v26, v114
	v_add_f32_e32 v26, v26, v115
	v_add_f32_e32 v26, v26, v116
	v_add_f32_e32 v26, v26, v117
	v_add_f32_e32 v26, v26, v118
	v_add_f32_e32 v26, v26, v119
	v_add_f32_e32 v151, v151, v26
	v_cvt_pk_bf16_f32 v128, v104, v105
	v_cvt_pk_bf16_f32 v129, v106, v107
	v_cvt_pk_bf16_f32 v130, v108, v109
	v_cvt_pk_bf16_f32 v131, v110, v111
	v_cvt_pk_bf16_f32 v152, v112, v113
	v_cvt_pk_bf16_f32 v153, v114, v115
	v_cvt_pk_bf16_f32 v154, v116, v117
	v_cvt_pk_bf16_f32 v155, v118, v119
	v_mov_b32_e32 v156, v165
	v_add_f32_e32 v157, 0x3f800000, v165
	v_add_f32_e32 v158, 0x40000000, v165
	v_add_f32_e32 v159, 0x40400000, v165
	v_add_f32_e32 v160, 0x41800000, v165
	v_add_f32_e32 v161, 0x41880000, v165
	v_add_f32_e32 v162, 0x41900000, v165
	v_add_f32_e32 v163, 0x41980000, v165
	v_add_f32_e32 v176, 0x42000000, v165
	v_add_f32_e32 v177, 0x42040000, v165
	v_add_f32_e32 v178, 0x42080000, v165
	v_add_f32_e32 v179, 0x420c0000, v165
	v_add_f32_e32 v180, 0x42400000, v165
	v_add_f32_e32 v181, 0x42440000, v165
	v_add_f32_e32 v182, 0x42480000, v165
	v_add_f32_e32 v183, 0x424c0000, v165
	v_fma_f32 v204, -v150, |v156|, v25
	v_fma_f32 v205, -v150, |v157|, v25
	v_fma_f32 v206, -v150, |v158|, v25
	v_fma_f32 v207, -v150, |v159|, v25
	v_fma_f32 v208, -v150, |v160|, v25
	v_fma_f32 v209, -v150, |v161|, v25
	v_fma_f32 v210, -v150, |v162|, v25
	v_fma_f32 v211, -v150, |v163|, v25
	v_fma_f32 v184, -v150, |v176|, v25
	v_fma_f32 v185, -v150, |v177|, v25
	v_fma_f32 v186, -v150, |v178|, v25
	v_fma_f32 v187, -v150, |v179|, v25
	v_fma_f32 v188, -v150, |v180|, v25
	v_fma_f32 v189, -v150, |v181|, v25
	v_fma_f32 v190, -v150, |v182|, v25
	v_fma_f32 v191, -v150, |v183|, v25
	v_fma_f32 v156, -v150, |v156|, v24
	v_fma_f32 v157, -v150, |v157|, v24
	v_fma_f32 v158, -v150, |v158|, v24
	v_fma_f32 v159, -v150, |v159|, v24
	v_fma_f32 v160, -v150, |v160|, v24
	v_fma_f32 v161, -v150, |v161|, v24
	v_fma_f32 v162, -v150, |v162|, v24
	v_fma_f32 v163, -v150, |v163|, v24
	v_fma_f32 v176, -v150, |v176|, v24
	v_fma_f32 v177, -v150, |v177|, v24
	v_fma_f32 v178, -v150, |v178|, v24
	v_fma_f32 v179, -v150, |v179|, v24
	v_fma_f32 v180, -v150, |v180|, v24
	v_fma_f32 v181, -v150, |v181|, v24
	v_fma_f32 v182, -v150, |v182|, v24
	v_fma_f32 v183, -v150, |v183|, v24
	ds_read_b128 v[244:247], v255 offset:9216
	s_waitcnt lgkmcnt(4)
	v_mfma_f32_16x16x32_bf16 v[88:91], v[228:231], v[4:7], v[156:159]
	ds_read_b128 v[248:251], v255 offset:9280
	s_waitcnt lgkmcnt(4)
	v_mfma_f32_16x16x32_bf16 v[88:91], v[232:235], v[8:11], v[88:91]
	ds_read_b128 v[228:231], v255 offset:13824
	s_waitcnt lgkmcnt(4)
	v_mfma_f32_16x16x32_bf16 v[92:95], v[236:239], v[4:7], v[160:163]
	ds_read_b128 v[232:235], v255 offset:13888
	s_waitcnt lgkmcnt(4)
	v_mfma_f32_16x16x32_bf16 v[92:95], v[240:243], v[8:11], v[92:95]
	ds_read_b128 v[236:239], v255 offset:128
	s_waitcnt lgkmcnt(4)
	v_mfma_f32_16x16x32_bf16 v[96:99], v[244:247], v[4:7], v[176:179]
	ds_read_b128 v[240:243], v255 offset:192
	s_waitcnt lgkmcnt(4)
	v_mfma_f32_16x16x32_bf16 v[96:99], v[248:251], v[8:11], v[96:99]
	ds_read_b128 v[244:247], v255 offset:4736
	s_waitcnt lgkmcnt(4)
	v_mfma_f32_16x16x32_bf16 v[100:103], v[228:231], v[4:7], v[180:183]
	ds_read_b128 v[248:251], v255 offset:4800
	s_waitcnt lgkmcnt(4)
	v_mfma_f32_16x16x32_bf16 v[100:103], v[232:235], v[8:11], v[100:103]
	ds_read_b128 v[228:231], v255 offset:9344
	s_waitcnt lgkmcnt(4)
	v_mfma_f32_16x16x32_bf16 v[104:107], v[236:239], v[12:15], v[204:207]
	ds_read_b128 v[232:235], v255 offset:9408
	s_waitcnt lgkmcnt(4)
	v_mfma_f32_16x16x32_bf16 v[104:107], v[240:243], v[16:19], v[104:107]
	ds_read_b128 v[236:239], v255 offset:13952
	s_waitcnt lgkmcnt(4)
	v_mfma_f32_16x16x32_bf16 v[108:111], v[244:247], v[12:15], v[208:211]
	ds_read_b128 v[240:243], v255 offset:14016
	s_waitcnt lgkmcnt(4)
	v_mfma_f32_16x16x32_bf16 v[108:111], v[248:251], v[16:19], v[108:111]
	ds_read_b64_tr_b16 v[244:245], v174 offset:36864
	ds_read_b64_tr_b16 v[246:247], v174 offset:41472
	s_waitcnt lgkmcnt(5)
	v_mfma_f32_16x16x32_bf16 v[112:115], v[228:231], v[12:15], v[184:187]
	ds_read_b64_tr_b16 v[248:249], v174 offset:36896
	ds_read_b64_tr_b16 v[250:251], v174 offset:41504
	s_waitcnt lgkmcnt(6)
	v_mfma_f32_16x16x32_bf16 v[112:115], v[232:235], v[16:19], v[112:115]
	ds_read_b64_tr_b16 v[228:229], v174 offset:36928
	ds_read_b64_tr_b16 v[230:231], v174 offset:41536
	s_waitcnt lgkmcnt(7)
	v_mfma_f32_16x16x32_bf16 v[116:119], v[236:239], v[12:15], v[188:191]
	ds_read_b64_tr_b16 v[232:233], v174 offset:36960
	ds_read_b64_tr_b16 v[234:235], v174 offset:41568
	s_waitcnt lgkmcnt(8)
	v_mfma_f32_16x16x32_bf16 v[116:119], v[240:243], v[16:19], v[116:119]
	ds_read_b64_tr_b16 v[236:237], v174 offset:36992
	ds_read_b64_tr_b16 v[238:239], v174 offset:41600
	s_waitcnt lgkmcnt(8)
	v_mfma_f32_16x16x32_bf16 v[28:31], v[244:247], v[120:123], v[28:31]
	v_mfma_f32_16x16x32_bf16 v[36:39], v[244:247], v[128:131], v[36:39]
	ds_read_b64_tr_b16 v[240:241], v174 offset:37024
	ds_read_b64_tr_b16 v[242:243], v174 offset:41632
	s_waitcnt lgkmcnt(8)
	v_mfma_f32_16x16x32_bf16 v[32:35], v[248:251], v[120:123], v[32:35]
	v_mfma_f32_16x16x32_bf16 v[44:47], v[248:251], v[128:131], v[44:47]
	ds_read_b64_tr_b16 v[244:245], v174 offset:37056
	ds_read_b64_tr_b16 v[246:247], v174 offset:41664
	s_waitcnt lgkmcnt(8)
	v_mfma_f32_16x16x32_bf16 v[40:43], v[228:231], v[120:123], v[40:43]
	v_mfma_f32_16x16x32_bf16 v[48:51], v[228:231], v[128:131], v[48:51]
	ds_read_b64_tr_b16 v[248:249], v174 offset:37088
	ds_read_b64_tr_b16 v[250:251], v174 offset:41696
	s_waitcnt lgkmcnt(8)
	v_mfma_f32_16x16x32_bf16 v[52:55], v[232:235], v[120:123], v[52:55]
	v_mfma_f32_16x16x32_bf16 v[60:63], v[232:235], v[128:131], v[60:63]
	ds_read_b64_tr_b16 v[228:229], v174 offset:46080
	ds_read_b64_tr_b16 v[230:231], v174 offset:50688
	s_waitcnt lgkmcnt(8)
	v_mfma_f32_16x16x32_bf16 v[56:59], v[236:239], v[120:123], v[56:59]
	v_mfma_f32_16x16x32_bf16 v[68:71], v[236:239], v[128:131], v[68:71]
	ds_read_b64_tr_b16 v[232:233], v174 offset:46112
	ds_read_b64_tr_b16 v[234:235], v174 offset:50720
	s_waitcnt lgkmcnt(8)
	v_mfma_f32_16x16x32_bf16 v[64:67], v[240:243], v[120:123], v[64:67]
	v_mfma_f32_16x16x32_bf16 v[76:79], v[240:243], v[128:131], v[76:79]
	ds_read_b64_tr_b16 v[236:237], v174 offset:46144
	ds_read_b64_tr_b16 v[238:239], v174 offset:50752
	s_waitcnt lgkmcnt(8)
	v_mfma_f32_16x16x32_bf16 v[72:75], v[244:247], v[120:123], v[72:75]
	v_mfma_f32_16x16x32_bf16 v[80:83], v[244:247], v[128:131], v[80:83]
	ds_read_b64_tr_b16 v[240:241], v174 offset:46176
	ds_read_b64_tr_b16 v[242:243], v174 offset:50784
	s_waitcnt lgkmcnt(8)
	v_mfma_f32_16x16x32_bf16 v[84:87], v[248:251], v[120:123], v[84:87]
	v_mfma_f32_16x16x32_bf16 v[20:23], v[248:251], v[128:131], v[20:23]
	ds_read_b64_tr_b16 v[244:245], v174 offset:46208
	ds_read_b64_tr_b16 v[246:247], v174 offset:50816
	s_waitcnt lgkmcnt(8)
	v_mfma_f32_16x16x32_bf16 v[28:31], v[228:231], v[124:127], v[28:31]
	v_mfma_f32_16x16x32_bf16 v[36:39], v[228:231], v[152:155], v[36:39]
	ds_read_b64_tr_b16 v[248:249], v174 offset:46240
	ds_read_b64_tr_b16 v[250:251], v174 offset:50848
	s_waitcnt lgkmcnt(8)
	v_mfma_f32_16x16x32_bf16 v[32:35], v[232:235], v[124:127], v[32:35]
	v_mfma_f32_16x16x32_bf16 v[44:47], v[232:235], v[152:155], v[44:47]
	ds_read_b64_tr_b16 v[228:229], v174 offset:46272
	ds_read_b64_tr_b16 v[230:231], v174 offset:50880
	s_waitcnt lgkmcnt(8)
	v_mfma_f32_16x16x32_bf16 v[40:43], v[236:239], v[124:127], v[40:43]
	v_mfma_f32_16x16x32_bf16 v[48:51], v[236:239], v[152:155], v[48:51]
	ds_read_b64_tr_b16 v[232:233], v174 offset:46304
	ds_read_b64_tr_b16 v[234:235], v174 offset:50912
	s_waitcnt lgkmcnt(8)
	v_mfma_f32_16x16x32_bf16 v[52:55], v[240:243], v[124:127], v[52:55]
	v_mfma_f32_16x16x32_bf16 v[60:63], v[240:243], v[152:155], v[60:63]
	s_waitcnt lgkmcnt(6)
	v_mfma_f32_16x16x32_bf16 v[56:59], v[244:247], v[124:127], v[56:59]
	v_mfma_f32_16x16x32_bf16 v[68:71], v[244:247], v[152:155], v[68:71]
	s_waitcnt lgkmcnt(4)
	v_mfma_f32_16x16x32_bf16 v[64:67], v[248:251], v[124:127], v[64:67]
	v_mfma_f32_16x16x32_bf16 v[76:79], v[248:251], v[152:155], v[76:79]
	s_waitcnt lgkmcnt(2)
	v_mfma_f32_16x16x32_bf16 v[72:75], v[228:231], v[124:127], v[72:75]
	v_mfma_f32_16x16x32_bf16 v[80:83], v[228:231], v[152:155], v[80:83]
	s_waitcnt lgkmcnt(0)
	v_mfma_f32_16x16x32_bf16 v[84:87], v[232:235], v[124:127], v[84:87]
	v_mfma_f32_16x16x32_bf16 v[20:23], v[232:235], v[152:155], v[20:23]
	s_waitcnt vmcnt(4)
	ds_write_b128 v169, v[138:141] offset:18432
	ds_write_b128 v169, v[142:145] offset:27648
	ds_write_b128 v164, v[146:149] offset:36864
	ds_write_b128 v164, v[194:197] offset:46080
	s_mov_b32 s31, s38
	s_mov_b32 s38, s39
	s_add_i32 s39, s39, 0x4800
	s_cmp_lg_u32 s39, 0xd800
	s_cselect_b32 s39, s39, 0
	s_mov_b32 s66, 0xff800000
	s_cmp_ge_u32 s5, 1
	s_cselect_b32 s66, 0x42800000, s66
	s_add_i32 s5, s5, 1
	s_add_i32 s8, s5, 2
	s_min_u32 s8, s8, 63
	s_mul_i32 s30, s8, 0xf8000
	v_add_f32_e32 v165, 0x42800000, v165
	v_add_u32_e32 v174, s31, v168
	v_add_u32_e32 v164, s39, v169
	s_add_u32 s80, s42, s30
	s_addc_u32 s81, s43, 0
	s_add_u32 s86, s80, 0x7c000
	s_addc_u32 s87, s81, 0
	s_add_u32 s96, s46, s30
	s_addc_u32 s97, s47, 0
	s_add_u32 s98, s96, 0x7c000
	s_addc_u32 s99, s97, 0
	s_waitcnt lgkmcnt(0)
	s_barrier
	global_load_dwordx4 v[138:141], v173, s[80:81]
	global_load_dwordx4 v[146:149], v175, s[96:97]
	global_load_dwordx4 v[142:145], v173, s[86:87]
	global_load_dwordx4 v[194:197], v175, s[98:99]
	ds_read_b128 v[228:231], v255 offset:18432
	ds_read_b128 v[232:235], v255 offset:18496
	ds_read_b128 v[236:239], v255 offset:23040
	ds_read_b128 v[240:243], v255 offset:23104
	v_max3_f32 v26, v88, v89, v90
	v_max3_f32 v26, v26, v91, v92
	v_max3_f32 v26, v26, v93, v94
	v_max3_f32 v26, v26, v95, v96
	v_max3_f32 v26, v26, v97, v98
	v_max3_f32 v26, v26, v99, v100
	v_max3_f32 v26, v26, v101, v102
	v_max_f32_e32 v26, v26, v103
	v_cmp_lt_f32_e32 vcc, s66, v26
	s_cbranch_vccz .Ld_nr_B1_0
	v_mov_b32_e32 v27, v26
	s_nop 1
	v_permlane16_swap_b32_e32 v26, v27
	v_max_f32_e32 v26, v26, v27
	v_mov_b32_e32 v27, v26
	s_nop 1
	v_permlane32_swap_b32_e32 v26, v27
	v_max_f32_e32 v26, v26, v27
	v_cmp_lt_f32_e32 vcc, s66, v26
	s_nop 1
	v_cndmask_b32_e32 v3, 0, v26, vcc
	v_sub_f32_e32 v2, 0, v3
	v_min_f32_e32 v2, 0, v2
	v_exp_f32_e32 v2, v2
	v_sub_f32_e32 v24, v24, v3
	v_mul_f32_e32 v0, v0, v2
	v_mul_f32_e32 v28, v28, v2
	v_mul_f32_e32 v29, v29, v2
	v_mul_f32_e32 v30, v30, v2
	v_mul_f32_e32 v31, v31, v2
	v_mul_f32_e32 v32, v32, v2
	v_mul_f32_e32 v33, v33, v2
	v_mul_f32_e32 v34, v34, v2
	v_mul_f32_e32 v35, v35, v2
	v_mul_f32_e32 v40, v40, v2
	v_mul_f32_e32 v41, v41, v2
	v_mul_f32_e32 v42, v42, v2
	v_mul_f32_e32 v43, v43, v2
	v_mul_f32_e32 v52, v52, v2
	v_mul_f32_e32 v53, v53, v2
	v_mul_f32_e32 v54, v54, v2
	v_mul_f32_e32 v55, v55, v2
	v_mul_f32_e32 v56, v56, v2
	v_mul_f32_e32 v57, v57, v2
	v_mul_f32_e32 v58, v58, v2
	v_mul_f32_e32 v59, v59, v2
	v_mul_f32_e32 v64, v64, v2
	v_mul_f32_e32 v65, v65, v2
	v_mul_f32_e32 v66, v66, v2
	v_mul_f32_e32 v67, v67, v2
	v_mul_f32_e32 v72, v72, v2
	v_mul_f32_e32 v73, v73, v2
	v_mul_f32_e32 v74, v74, v2
	v_mul_f32_e32 v75, v75, v2
	v_mul_f32_e32 v84, v84, v2
	v_mul_f32_e32 v85, v85, v2
	v_mul_f32_e32 v86, v86, v2
	v_mul_f32_e32 v87, v87, v2
	v_sub_f32_e32 v88, v88, v3
	v_sub_f32_e32 v89, v89, v3
	v_sub_f32_e32 v90, v90, v3
	v_sub_f32_e32 v91, v91, v3
	v_sub_f32_e32 v92, v92, v3
	v_sub_f32_e32 v93, v93, v3
	v_sub_f32_e32 v94, v94, v3
	v_sub_f32_e32 v95, v95, v3
	v_sub_f32_e32 v96, v96, v3
	v_sub_f32_e32 v97, v97, v3
	v_sub_f32_e32 v98, v98, v3
	v_sub_f32_e32 v99, v99, v3
	v_sub_f32_e32 v100, v100, v3
	v_sub_f32_e32 v101, v101, v3
	v_sub_f32_e32 v102, v102, v3
	v_sub_f32_e32 v103, v103, v3

.Ld_nr_B1_1:
	v_exp_f32_e32 v104, v104
	v_exp_f32_e32 v105, v105
	v_exp_f32_e32 v106, v106
	v_exp_f32_e32 v107, v107
	v_exp_f32_e32 v108, v108
	v_exp_f32_e32 v109, v109
	v_exp_f32_e32 v110, v110
	v_exp_f32_e32 v111, v111
	v_exp_f32_e32 v112, v112
	v_exp_f32_e32 v113, v113
	v_exp_f32_e32 v114, v114
	v_exp_f32_e32 v115, v115
	v_exp_f32_e32 v116, v116
	v_exp_f32_e32 v117, v117
	v_exp_f32_e32 v118, v118
	v_exp_f32_e32 v119, v119
	s_nop 0
	v_add_f32_e32 v26, v104, v105
	v_add_f32_e32 v26, v26, v106
	v_add_f32_e32 v26, v26, v107
	v_add_f32_e32 v26, v26, v108
	v_add_f32_e32 v26, v26, v109
	v_add_f32_e32 v26, v26, v110
	v_add_f32_e32 v26, v26, v111
	v_add_f32_e32 v26, v26, v112
	v_add_f32_e32 v26, v26, v113
	v_add_f32_e32 v26, v26, v114
	v_add_f32_e32 v26, v26, v115
	v_add_f32_e32 v26, v26, v116
	v_add_f32_e32 v26, v26, v117
	v_add_f32_e32 v26, v26, v118
	v_add_f32_e32 v26, v26, v119
	v_add_f32_e32 v151, v151, v26
	v_cvt_pk_bf16_f32 v128, v104, v105
	v_cvt_pk_bf16_f32 v129, v106, v107
	v_cvt_pk_bf16_f32 v130, v108, v109
	v_cvt_pk_bf16_f32 v131, v110, v111
	v_cvt_pk_bf16_f32 v152, v112, v113
	v_cvt_pk_bf16_f32 v153, v114, v115
	v_cvt_pk_bf16_f32 v154, v116, v117
	v_cvt_pk_bf16_f32 v155, v118, v119
	v_mov_b32_e32 v156, v165
	v_add_f32_e32 v157, 0x3f800000, v165
	v_add_f32_e32 v158, 0x40000000, v165
	v_add_f32_e32 v159, 0x40400000, v165
	v_add_f32_e32 v160, 0x41800000, v165
	v_add_f32_e32 v161, 0x41880000, v165
	v_add_f32_e32 v162, 0x41900000, v165
	v_add_f32_e32 v163, 0x41980000, v165
	v_add_f32_e32 v176, 0x42000000, v165
	v_add_f32_e32 v177, 0x42040000, v165
	v_add_f32_e32 v178, 0x42080000, v165
	v_add_f32_e32 v179, 0x420c0000, v165
	v_add_f32_e32 v180, 0x42400000, v165
	v_add_f32_e32 v181, 0x42440000, v165
	v_add_f32_e32 v182, 0x42480000, v165
	v_add_f32_e32 v183, 0x424c0000, v165
	v_fma_f32 v204, -v150, |v156|, v25
	v_fma_f32 v205, -v150, |v157|, v25
	v_fma_f32 v206, -v150, |v158|, v25
	v_fma_f32 v207, -v150, |v159|, v25
	v_fma_f32 v208, -v150, |v160|, v25
	v_fma_f32 v209, -v150, |v161|, v25
	v_fma_f32 v210, -v150, |v162|, v25
	v_fma_f32 v211, -v150, |v163|, v25
	v_fma_f32 v184, -v150, |v176|, v25
	v_fma_f32 v185, -v150, |v177|, v25
	v_fma_f32 v186, -v150, |v178|, v25
	v_fma_f32 v187, -v150, |v179|, v25
	v_fma_f32 v188, -v150, |v180|, v25
	v_fma_f32 v189, -v150, |v181|, v25
	v_fma_f32 v190, -v150, |v182|, v25
	v_fma_f32 v191, -v150, |v183|, v25
	v_fma_f32 v156, -v150, |v156|, v24
	v_fma_f32 v157, -v150, |v157|, v24
	v_fma_f32 v158, -v150, |v158|, v24
	v_fma_f32 v159, -v150, |v159|, v24
	v_fma_f32 v160, -v150, |v160|, v24
	v_fma_f32 v161, -v150, |v161|, v24
	v_fma_f32 v162, -v150, |v162|, v24
	v_fma_f32 v163, -v150, |v163|, v24
	v_fma_f32 v176, -v150, |v176|, v24
	v_fma_f32 v177, -v150, |v177|, v24
	v_fma_f32 v178, -v150, |v178|, v24
	v_fma_f32 v179, -v150, |v179|, v24
	v_fma_f32 v180, -v150, |v180|, v24
	v_fma_f32 v181, -v150, |v181|, v24
	v_fma_f32 v182, -v150, |v182|, v24
	v_fma_f32 v183, -v150, |v183|, v24
	ds_read_b128 v[244:247], v255 offset:27648
	s_waitcnt lgkmcnt(4)
	v_mfma_f32_16x16x32_bf16 v[88:91], v[228:231], v[4:7], v[156:159]
	ds_read_b128 v[248:251], v255 offset:27712
	s_waitcnt lgkmcnt(4)
	v_mfma_f32_16x16x32_bf16 v[88:91], v[232:235], v[8:11], v[88:91]
	ds_read_b128 v[228:231], v255 offset:32256
	s_waitcnt lgkmcnt(4)
	v_mfma_f32_16x16x32_bf16 v[92:95], v[236:239], v[4:7], v[160:163]
	ds_read_b128 v[232:235], v255 offset:32320
	s_waitcnt lgkmcnt(4)
	v_mfma_f32_16x16x32_bf16 v[92:95], v[240:243], v[8:11], v[92:95]
	ds_read_b128 v[236:239], v255 offset:18560
	s_waitcnt lgkmcnt(4)
	v_mfma_f32_16x16x32_bf16 v[96:99], v[244:247], v[4:7], v[176:179]
	ds_read_b128 v[240:243], v255 offset:18624
	s_waitcnt lgkmcnt(4)
	v_mfma_f32_16x16x32_bf16 v[96:99], v[248:251], v[8:11], v[96:99]
	ds_read_b128 v[244:247], v255 offset:23168
	s_waitcnt lgkmcnt(4)
	v_mfma_f32_16x16x32_bf16 v[100:103], v[228:231], v[4:7], v[180:183]
	ds_read_b128 v[248:251], v255 offset:23232
	s_waitcnt lgkmcnt(4)
	v_mfma_f32_16x16x32_bf16 v[100:103], v[232:235], v[8:11], v[100:103]
	ds_read_b128 v[228:231], v255 offset:27776
	s_waitcnt lgkmcnt(4)
	v_mfma_f32_16x16x32_bf16 v[104:107], v[236:239], v[12:15], v[204:207]
	ds_read_b128 v[232:235], v255 offset:27840
	s_waitcnt lgkmcnt(4)
	v_mfma_f32_16x16x32_bf16 v[104:107], v[240:243], v[16:19], v[104:107]
	ds_read_b128 v[236:239], v255 offset:32384
	s_waitcnt lgkmcnt(4)
	v_mfma_f32_16x16x32_bf16 v[108:111], v[244:247], v[12:15], v[208:211]
	ds_read_b128 v[240:243], v255 offset:32448
	s_waitcnt lgkmcnt(4)
	v_mfma_f32_16x16x32_bf16 v[108:111], v[248:251], v[16:19], v[108:111]
	ds_read_b64_tr_b16 v[244:245], v174 offset:36864
	ds_read_b64_tr_b16 v[246:247], v174 offset:41472
	s_waitcnt lgkmcnt(5)
	v_mfma_f32_16x16x32_bf16 v[112:115], v[228:231], v[12:15], v[184:187]
	ds_read_b64_tr_b16 v[248:249], v174 offset:36896
	ds_read_b64_tr_b16 v[250:251], v174 offset:41504
	s_waitcnt lgkmcnt(6)
	v_mfma_f32_16x16x32_bf16 v[112:115], v[232:235], v[16:19], v[112:115]
	ds_read_b64_tr_b16 v[228:229], v174 offset:36928
	ds_read_b64_tr_b16 v[230:231], v174 offset:41536
	s_waitcnt lgkmcnt(7)
	v_mfma_f32_16x16x32_bf16 v[116:119], v[236:239], v[12:15], v[188:191]
	ds_read_b64_tr_b16 v[232:233], v174 offset:36960
	ds_read_b64_tr_b16 v[234:235], v174 offset:41568
	s_waitcnt lgkmcnt(8)
	v_mfma_f32_16x16x32_bf16 v[116:119], v[240:243], v[16:19], v[116:119]
	ds_read_b64_tr_b16 v[236:237], v174 offset:36992
	ds_read_b64_tr_b16 v[238:239], v174 offset:41600
	s_waitcnt lgkmcnt(8)
	v_mfma_f32_16x16x32_bf16 v[28:31], v[244:247], v[120:123], v[28:31]
	v_mfma_f32_16x16x32_bf16 v[36:39], v[244:247], v[128:131], v[36:39]
	ds_read_b64_tr_b16 v[240:241], v174 offset:37024
	ds_read_b64_tr_b16 v[242:243], v174 offset:41632
	s_waitcnt lgkmcnt(8)
	v_mfma_f32_16x16x32_bf16 v[32:35], v[248:251], v[120:123], v[32:35]
	v_mfma_f32_16x16x32_bf16 v[44:47], v[248:251], v[128:131], v[44:47]
	ds_read_b64_tr_b16 v[244:245], v174 offset:37056
	ds_read_b64_tr_b16 v[246:247], v174 offset:41664
	s_waitcnt lgkmcnt(8)
	v_mfma_f32_16x16x32_bf16 v[40:43], v[228:231], v[120:123], v[40:43]
	v_mfma_f32_16x16x32_bf16 v[48:51], v[228:231], v[128:131], v[48:51]
	ds_read_b64_tr_b16 v[248:249], v174 offset:37088
	ds_read_b64_tr_b16 v[250:251], v174 offset:41696
	s_waitcnt lgkmcnt(8)
	v_mfma_f32_16x16x32_bf16 v[52:55], v[232:235], v[120:123], v[52:55]
	v_mfma_f32_16x16x32_bf16 v[60:63], v[232:235], v[128:131], v[60:63]
	ds_read_b64_tr_b16 v[228:229], v174 offset:46080
	ds_read_b64_tr_b16 v[230:231], v174 offset:50688
	s_waitcnt lgkmcnt(8)
	v_mfma_f32_16x16x32_bf16 v[56:59], v[236:239], v[120:123], v[56:59]
	v_mfma_f32_16x16x32_bf16 v[68:71], v[236:239], v[128:131], v[68:71]
	ds_read_b64_tr_b16 v[232:233], v174 offset:46112
	ds_read_b64_tr_b16 v[234:235], v174 offset:50720
	s_waitcnt lgkmcnt(8)
	v_mfma_f32_16x16x32_bf16 v[64:67], v[240:243], v[120:123], v[64:67]
	v_mfma_f32_16x16x32_bf16 v[76:79], v[240:243], v[128:131], v[76:79]
	ds_read_b64_tr_b16 v[236:237], v174 offset:46144
	ds_read_b64_tr_b16 v[238:239], v174 offset:50752
	s_waitcnt lgkmcnt(8)
	v_mfma_f32_16x16x32_bf16 v[72:75], v[244:247], v[120:123], v[72:75]
	v_mfma_f32_16x16x32_bf16 v[80:83], v[244:247], v[128:131], v[80:83]
	ds_read_b64_tr_b16 v[240:241], v174 offset:46176
	ds_read_b64_tr_b16 v[242:243], v174 offset:50784
	s_waitcnt lgkmcnt(8)
	v_mfma_f32_16x16x32_bf16 v[84:87], v[248:251], v[120:123], v[84:87]
	v_mfma_f32_16x16x32_bf16 v[20:23], v[248:251], v[128:131], v[20:23]
	ds_read_b64_tr_b16 v[244:245], v174 offset:46208
	ds_read_b64_tr_b16 v[246:247], v174 offset:50816
	s_waitcnt lgkmcnt(8)
	v_mfma_f32_16x16x32_bf16 v[28:31], v[228:231], v[124:127], v[28:31]
	v_mfma_f32_16x16x32_bf16 v[36:39], v[228:231], v[152:155], v[36:39]
	ds_read_b64_tr_b16 v[248:249], v174 offset:46240
	ds_read_b64_tr_b16 v[250:251], v174 offset:50848
	s_waitcnt lgkmcnt(8)
	v_mfma_f32_16x16x32_bf16 v[32:35], v[232:235], v[124:127], v[32:35]
	v_mfma_f32_16x16x32_bf16 v[44:47], v[232:235], v[152:155], v[44:47]
	ds_read_b64_tr_b16 v[228:229], v174 offset:46272
	ds_read_b64_tr_b16 v[230:231], v174 offset:50880
	s_waitcnt lgkmcnt(8)
	v_mfma_f32_16x16x32_bf16 v[40:43], v[236:239], v[124:127], v[40:43]
	v_mfma_f32_16x16x32_bf16 v[48:51], v[236:239], v[152:155], v[48:51]
	ds_read_b64_tr_b16 v[232:233], v174 offset:46304
	ds_read_b64_tr_b16 v[234:235], v174 offset:50912
	s_waitcnt lgkmcnt(8)
	v_mfma_f32_16x16x32_bf16 v[52:55], v[240:243], v[124:127], v[52:55]
	v_mfma_f32_16x16x32_bf16 v[60:63], v[240:243], v[152:155], v[60:63]
	s_waitcnt lgkmcnt(6)
	v_mfma_f32_16x16x32_bf16 v[56:59], v[244:247], v[124:127], v[56:59]
	v_mfma_f32_16x16x32_bf16 v[68:71], v[244:247], v[152:155], v[68:71]
	s_waitcnt lgkmcnt(4)
	v_mfma_f32_16x16x32_bf16 v[64:67], v[248:251], v[124:127], v[64:67]
	v_mfma_f32_16x16x32_bf16 v[76:79], v[248:251], v[152:155], v[76:79]
	s_waitcnt lgkmcnt(2)
	v_mfma_f32_16x16x32_bf16 v[72:75], v[228:231], v[124:127], v[72:75]
	v_mfma_f32_16x16x32_bf16 v[80:83], v[228:231], v[152:155], v[80:83]
	s_waitcnt lgkmcnt(0)
	v_mfma_f32_16x16x32_bf16 v[84:87], v[232:235], v[124:127], v[84:87]
	v_mfma_f32_16x16x32_bf16 v[20:23], v[232:235], v[152:155], v[20:23]
	s_waitcnt vmcnt(4)
	ds_write_b128 v169, v[212:215] offset:0
	ds_write_b128 v169, v[216:219] offset:9216
	ds_write_b128 v164, v[220:223] offset:36864
	ds_write_b128 v164, v[224:227] offset:46080
	s_mov_b32 s31, s38
	s_mov_b32 s38, s39
	s_add_i32 s39, s39, 0x4800
	s_cmp_lg_u32 s39, 0xd800
	s_cselect_b32 s39, s39, 0
	s_mov_b32 s66, 0xff800000
	s_cmp_ge_u32 s5, 1
	s_cselect_b32 s66, 0x42800000, s66
	s_add_i32 s5, s5, 1
	s_add_i32 s8, s5, 2
	s_min_u32 s8, s8, 63
	s_mul_i32 s30, s8, 0xf8000
	v_add_f32_e32 v165, 0x42800000, v165
	v_add_u32_e32 v174, s31, v168
	v_add_u32_e32 v164, s39, v169
	s_add_u32 s80, s42, s30
	s_addc_u32 s81, s43, 0
	s_add_u32 s86, s80, 0x7c000
	s_addc_u32 s87, s81, 0
	s_add_u32 s96, s46, s30
	s_addc_u32 s97, s47, 0
	s_add_u32 s98, s96, 0x7c000
	s_addc_u32 s99, s97, 0
	s_waitcnt lgkmcnt(0)
	s_barrier
	s_cmp_lt_u32 s5, 64
	s_cbranch_scc1 .Ld_loopB
	v_add_u32_e32 v174, s31, v168
	ds_read_b64_tr_b16 v[228:229], v174 offset:36864
	ds_read_b64_tr_b16 v[230:231], v174 offset:41472
	ds_read_b64_tr_b16 v[232:233], v174 offset:36896
	ds_read_b64_tr_b16 v[234:235], v174 offset:41504
	ds_read_b64_tr_b16 v[236:237], v174 offset:36928
	ds_read_b64_tr_b16 v[238:239], v174 offset:41536
	ds_read_b64_tr_b16 v[240:241], v174 offset:36960
	ds_read_b64_tr_b16 v[242:243], v174 offset:41568
	v_max3_f32 v26, v88, v89, v90
	v_max3_f32 v26, v26, v91, v92
	v_max3_f32 v26, v26, v93, v94
	v_max3_f32 v26, v26, v95, v96
	v_max3_f32 v26, v26, v97, v98
	v_max3_f32 v26, v26, v99, v100
	v_max3_f32 v26, v26, v101, v102
	v_max_f32_e32 v26, v26, v103
	v_cmp_lt_f32_e32 vcc, s66, v26
	s_cbranch_vccz .Ld_nr_Bt_0
	v_mov_b32_e32 v27, v26
	s_nop 1
	v_permlane16_swap_b32_e32 v26, v27
	v_max_f32_e32 v26, v26, v27
	v_mov_b32_e32 v27, v26
	s_nop 1
	v_permlane32_swap_b32_e32 v26, v27
	v_max_f32_e32 v26, v26, v27
	v_cmp_lt_f32_e32 vcc, s66, v26
	s_nop 1
	v_cndmask_b32_e32 v3, 0, v26, vcc
	v_sub_f32_e32 v2, 0, v3
	v_min_f32_e32 v2, 0, v2
	v_exp_f32_e32 v2, v2
	v_sub_f32_e32 v24, v24, v3
	v_mul_f32_e32 v0, v0, v2
	v_mul_f32_e32 v28, v28, v2
	v_mul_f32_e32 v29, v29, v2
	v_mul_f32_e32 v30, v30, v2
	v_mul_f32_e32 v31, v31, v2
	v_mul_f32_e32 v32, v32, v2
	v_mul_f32_e32 v33, v33, v2
	v_mul_f32_e32 v34, v34, v2
	v_mul_f32_e32 v35, v35, v2
	v_mul_f32_e32 v40, v40, v2
	v_mul_f32_e32 v41, v41, v2
	v_mul_f32_e32 v42, v42, v2
	v_mul_f32_e32 v43, v43, v2
	v_mul_f32_e32 v52, v52, v2
	v_mul_f32_e32 v53, v53, v2
	v_mul_f32_e32 v54, v54, v2
	v_mul_f32_e32 v55, v55, v2
	v_mul_f32_e32 v56, v56, v2
	v_mul_f32_e32 v57, v57, v2
	v_mul_f32_e32 v58, v58, v2
	v_mul_f32_e32 v59, v59, v2
	v_mul_f32_e32 v64, v64, v2
	v_mul_f32_e32 v65, v65, v2
	v_mul_f32_e32 v66, v66, v2
	v_mul_f32_e32 v67, v67, v2
	v_mul_f32_e32 v72, v72, v2
	v_mul_f32_e32 v73, v73, v2
	v_mul_f32_e32 v74, v74, v2
	v_mul_f32_e32 v75, v75, v2
	v_mul_f32_e32 v84, v84, v2
	v_mul_f32_e32 v85, v85, v2
	v_mul_f32_e32 v86, v86, v2
	v_mul_f32_e32 v87, v87, v2
	v_sub_f32_e32 v88, v88, v3
	v_sub_f32_e32 v89, v89, v3
	v_sub_f32_e32 v90, v90, v3
	v_sub_f32_e32 v91, v91, v3
	v_sub_f32_e32 v92, v92, v3
	v_sub_f32_e32 v93, v93, v3
	v_sub_f32_e32 v94, v94, v3
	v_sub_f32_e32 v95, v95, v3
	v_sub_f32_e32 v96, v96, v3
	v_sub_f32_e32 v97, v97, v3
	v_sub_f32_e32 v98, v98, v3
	v_sub_f32_e32 v99, v99, v3
	v_sub_f32_e32 v100, v100, v3
	v_sub_f32_e32 v101, v101, v3
	v_sub_f32_e32 v102, v102, v3
	v_sub_f32_e32 v103, v103, v3

.Ld_nr_Bt_1:
	v_exp_f32_e32 v104, v104
	v_exp_f32_e32 v105, v105
	v_exp_f32_e32 v106, v106
	v_exp_f32_e32 v107, v107
	v_exp_f32_e32 v108, v108
	v_exp_f32_e32 v109, v109
	v_exp_f32_e32 v110, v110
	v_exp_f32_e32 v111, v111
	v_exp_f32_e32 v112, v112
	v_exp_f32_e32 v113, v113
	v_exp_f32_e32 v114, v114
	v_exp_f32_e32 v115, v115
	v_exp_f32_e32 v116, v116
	v_exp_f32_e32 v117, v117
	v_exp_f32_e32 v118, v118
	v_exp_f32_e32 v119, v119
	s_nop 0
	v_add_f32_e32 v26, v104, v105
	v_add_f32_e32 v26, v26, v106
	v_add_f32_e32 v26, v26, v107
	v_add_f32_e32 v26, v26, v108
	v_add_f32_e32 v26, v26, v109
	v_add_f32_e32 v26, v26, v110
	v_add_f32_e32 v26, v26, v111
	v_add_f32_e32 v26, v26, v112
	v_add_f32_e32 v26, v26, v113
	v_add_f32_e32 v26, v26, v114
	v_add_f32_e32 v26, v26, v115
	v_add_f32_e32 v26, v26, v116
	v_add_f32_e32 v26, v26, v117
	v_add_f32_e32 v26, v26, v118
	v_add_f32_e32 v26, v26, v119
	v_add_f32_e32 v151, v151, v26
	v_cvt_pk_bf16_f32 v128, v104, v105
	v_cvt_pk_bf16_f32 v129, v106, v107
	v_cvt_pk_bf16_f32 v130, v108, v109
	v_cvt_pk_bf16_f32 v131, v110, v111
	v_cvt_pk_bf16_f32 v152, v112, v113
	v_cvt_pk_bf16_f32 v153, v114, v115
	v_cvt_pk_bf16_f32 v154, v116, v117
	v_cvt_pk_bf16_f32 v155, v118, v119
	ds_read_b64_tr_b16 v[244:245], v174 offset:36992
	ds_read_b64_tr_b16 v[246:247], v174 offset:41600
	s_waitcnt lgkmcnt(8)
	v_mfma_f32_16x16x32_bf16 v[28:31], v[228:231], v[120:123], v[28:31]
	v_mfma_f32_16x16x32_bf16 v[36:39], v[228:231], v[128:131], v[36:39]
	ds_read_b64_tr_b16 v[248:249], v174 offset:37024
	ds_read_b64_tr_b16 v[250:251], v174 offset:41632
	s_waitcnt lgkmcnt(8)
	v_mfma_f32_16x16x32_bf16 v[32:35], v[232:235], v[120:123], v[32:35]
	v_mfma_f32_16x16x32_bf16 v[44:47], v[232:235], v[128:131], v[44:47]
	ds_read_b64_tr_b16 v[228:229], v174 offset:37056
	ds_read_b64_tr_b16 v[230:231], v174 offset:41664
	s_waitcnt lgkmcnt(8)
	v_mfma_f32_16x16x32_bf16 v[40:43], v[236:239], v[120:123], v[40:43]
	v_mfma_f32_16x16x32_bf16 v[48:51], v[236:239], v[128:131], v[48:51]
	ds_read_b64_tr_b16 v[232:233], v174 offset:37088
	ds_read_b64_tr_b16 v[234:235], v174 offset:41696
	s_waitcnt lgkmcnt(8)
	v_mfma_f32_16x16x32_bf16 v[52:55], v[240:243], v[120:123], v[52:55]
	v_mfma_f32_16x16x32_bf16 v[60:63], v[240:243], v[128:131], v[60:63]
	ds_read_b64_tr_b16 v[236:237], v174 offset:46080
	ds_read_b64_tr_b16 v[238:239], v174 offset:50688
	s_waitcnt lgkmcnt(8)
	v_mfma_f32_16x16x32_bf16 v[56:59], v[244:247], v[120:123], v[56:59]
	v_mfma_f32_16x16x32_bf16 v[68:71], v[244:247], v[128:131], v[68:71]
	ds_read_b64_tr_b16 v[240:241], v174 offset:46112
	ds_read_b64_tr_b16 v[242:243], v174 offset:50720
	s_waitcnt lgkmcnt(8)
	v_mfma_f32_16x16x32_bf16 v[64:67], v[248:251], v[120:123], v[64:67]
	v_mfma_f32_16x16x32_bf16 v[76:79], v[248:251], v[128:131], v[76:79]
	ds_read_b64_tr_b16 v[244:245], v174 offset:46144
	ds_read_b64_tr_b16 v[246:247], v174 offset:50752
	s_waitcnt lgkmcnt(8)
	v_mfma_f32_16x16x32_bf16 v[72:75], v[228:231], v[120:123], v[72:75]
	v_mfma_f32_16x16x32_bf16 v[80:83], v[228:231], v[128:131], v[80:83]
	ds_read_b64_tr_b16 v[248:249], v174 offset:46176
	ds_read_b64_tr_b16 v[250:251], v174 offset:50784
	s_waitcnt lgkmcnt(8)
	v_mfma_f32_16x16x32_bf16 v[84:87], v[232:235], v[120:123], v[84:87]
	v_mfma_f32_16x16x32_bf16 v[20:23], v[232:235], v[128:131], v[20:23]
	ds_read_b64_tr_b16 v[228:229], v174 offset:46208
	ds_read_b64_tr_b16 v[230:231], v174 offset:50816
	s_waitcnt lgkmcnt(8)
	v_mfma_f32_16x16x32_bf16 v[28:31], v[236:239], v[124:127], v[28:31]
	v_mfma_f32_16x16x32_bf16 v[36:39], v[236:239], v[152:155], v[36:39]
	ds_read_b64_tr_b16 v[232:233], v174 offset:46240
	ds_read_b64_tr_b16 v[234:235], v174 offset:50848
	s_waitcnt lgkmcnt(8)
	v_mfma_f32_16x16x32_bf16 v[32:35], v[240:243], v[124:127], v[32:35]
	v_mfma_f32_16x16x32_bf16 v[44:47], v[240:243], v[152:155], v[44:47]
	ds_read_b64_tr_b16 v[236:237], v174 offset:46272
	ds_read_b64_tr_b16 v[238:239], v174 offset:50880
	s_waitcnt lgkmcnt(8)
	v_mfma_f32_16x16x32_bf16 v[40:43], v[244:247], v[124:127], v[40:43]
	v_mfma_f32_16x16x32_bf16 v[48:51], v[244:247], v[152:155], v[48:51]
	ds_read_b64_tr_b16 v[240:241], v174 offset:46304
	ds_read_b64_tr_b16 v[242:243], v174 offset:50912
	s_waitcnt lgkmcnt(8)
	v_mfma_f32_16x16x32_bf16 v[52:55], v[248:251], v[124:127], v[52:55]
	v_mfma_f32_16x16x32_bf16 v[60:63], v[248:251], v[152:155], v[60:63]
	s_waitcnt lgkmcnt(6)
	v_mfma_f32_16x16x32_bf16 v[56:59], v[228:231], v[124:127], v[56:59]
	v_mfma_f32_16x16x32_bf16 v[68:71], v[228:231], v[152:155], v[68:71]
	s_waitcnt lgkmcnt(4)
	v_mfma_f32_16x16x32_bf16 v[64:67], v[232:235], v[124:127], v[64:67]
	v_mfma_f32_16x16x32_bf16 v[76:79], v[232:235], v[152:155], v[76:79]
	s_waitcnt lgkmcnt(2)
	v_mfma_f32_16x16x32_bf16 v[72:75], v[236:239], v[124:127], v[72:75]
	v_mfma_f32_16x16x32_bf16 v[80:83], v[236:239], v[152:155], v[80:83]
	s_waitcnt lgkmcnt(0)
	v_mfma_f32_16x16x32_bf16 v[84:87], v[240:243], v[124:127], v[84:87]
	v_mfma_f32_16x16x32_bf16 v[20:23], v[240:243], v[152:155], v[20:23]
	s_waitcnt vmcnt(0)
	v_mov_b32_e32 v138, 0xa00
	v_mov_b32_e32 v139, 0x0
	v_mov_b32_e32 v140, 0x9ff
	v_mov_b32_e32 v141, 0x0
	v_mov_b32_e32 v142, 0x200
	v_mov_b32_e32 v143, 0x0
	v_mov_b32_e32 v144, 0x1ff
	v_mov_b32_e32 v145, 0x0
	v_mov_b32_e32 v146, 0xb00
	v_mov_b32_e32 v147, 0x0
	v_mov_b32_e32 v148, 0xaff
	v_mov_b32_e32 v149, 0x0
	v_mov_b32_e32 v194, 0x358637bd
	v_mov_b32_e32 v195, 0x2000
	v_mov_b32_e32 v196, 0x3e38aa3b
	v_mov_b32_e32 v197, 0x41b17218
	s_branch .LBB0_634
.Ld_groupA:
	v_mov_b32_e32 v28, 0
	v_mov_b32_e32 v29, 0
	v_mov_b32_e32 v30, 0
	v_mov_b32_e32 v31, 0
	v_mov_b32_e32 v32, 0
	v_mov_b32_e32 v33, 0
	v_mov_b32_e32 v34, 0
	v_mov_b32_e32 v35, 0
	v_mov_b32_e32 v40, 0
	v_mov_b32_e32 v41, 0
	v_mov_b32_e32 v42, 0
	v_mov_b32_e32 v43, 0
	v_mov_b32_e32 v52, 0
	v_mov_b32_e32 v53, 0
	v_mov_b32_e32 v54, 0
	v_mov_b32_e32 v55, 0
	v_mov_b32_e32 v56, 0
	v_mov_b32_e32 v57, 0
	v_mov_b32_e32 v58, 0
	v_mov_b32_e32 v59, 0
	v_mov_b32_e32 v64, 0
	v_mov_b32_e32 v65, 0
	v_mov_b32_e32 v66, 0
	v_mov_b32_e32 v67, 0
	v_mov_b32_e32 v72, 0
	v_mov_b32_e32 v73, 0
	v_mov_b32_e32 v74, 0
	v_mov_b32_e32 v75, 0
	v_mov_b32_e32 v84, 0
	v_mov_b32_e32 v85, 0
	v_mov_b32_e32 v86, 0
	v_mov_b32_e32 v87, 0
	v_mov_b32_e32 v36, 0
	v_mov_b32_e32 v37, 0
	v_mov_b32_e32 v38, 0
	v_mov_b32_e32 v39, 0
	v_mov_b32_e32 v44, 0
	v_mov_b32_e32 v45, 0
	v_mov_b32_e32 v46, 0
	v_mov_b32_e32 v47, 0
	v_mov_b32_e32 v48, 0
	v_mov_b32_e32 v49, 0
	v_mov_b32_e32 v50, 0
	v_mov_b32_e32 v51, 0
	v_mov_b32_e32 v60, 0
	v_mov_b32_e32 v61, 0
	v_mov_b32_e32 v62, 0
	v_mov_b32_e32 v63, 0
	v_mov_b32_e32 v68, 0
	v_mov_b32_e32 v69, 0
	v_mov_b32_e32 v70, 0
	v_mov_b32_e32 v71, 0
	v_mov_b32_e32 v76, 0
	v_mov_b32_e32 v77, 0
	v_mov_b32_e32 v78, 0
	v_mov_b32_e32 v79, 0
	v_mov_b32_e32 v80, 0
	v_mov_b32_e32 v81, 0
	v_mov_b32_e32 v82, 0
	v_mov_b32_e32 v83, 0
	v_mov_b32_e32 v20, 0
	v_mov_b32_e32 v21, 0
	v_mov_b32_e32 v22, 0
	v_mov_b32_e32 v23, 0
	v_mov_b32_e32 v120, 0
	v_mov_b32_e32 v121, 0
	v_mov_b32_e32 v122, 0
	v_mov_b32_e32 v123, 0
	v_mov_b32_e32 v124, 0
	v_mov_b32_e32 v125, 0
	v_mov_b32_e32 v126, 0
	v_mov_b32_e32 v127, 0
	v_mov_b32_e32 v128, 0
	v_mov_b32_e32 v129, 0
	v_mov_b32_e32 v130, 0
	v_mov_b32_e32 v131, 0
	v_mov_b32_e32 v152, 0
	v_mov_b32_e32 v153, 0
	v_mov_b32_e32 v154, 0
	v_mov_b32_e32 v155, 0
	v_mov_b32_e32 v0, 0
	v_mov_b32_e32 v151, 0
	v_mov_b32_e32 v24, 0
	v_mov_b32_e32 v25, 0
	s_mov_b32 s66, 0xff800000
	v_add_u32_e32 v255, v171, v172
	v_mov_b32_e32 v165, v170
	v_readfirstlane_b32 s42, v134
	v_readfirstlane_b32 s43, v135
	v_readfirstlane_b32 s46, v136
	v_readfirstlane_b32 s47, v137
	s_nop 3
	v_subrev_u32_e32 v173, s42, v134
	v_subrev_u32_e32 v175, s46, v136
	s_mov_b32 s5, 0
	s_mov_b32 s31, 0
	s_mov_b32 s38, 0
	s_mov_b32 s39, 0x4800
	s_mov_b32 s30, 0xf8000
	v_add_u32_e32 v174, s31, v168
	v_add_u32_e32 v164, s39, v169
	s_add_u32 s80, s42, s30
	s_addc_u32 s81, s43, 0
	s_add_u32 s86, s80, 0x7c000
	s_addc_u32 s87, s81, 0
	s_add_u32 s96, s46, s30
	s_addc_u32 s97, s47, 0
	s_add_u32 s98, s96, 0x7c000
	s_addc_u32 s99, s97, 0
	global_load_dwordx4 v[138:141], v173, s[80:81]
	global_load_dwordx4 v[146:149], v175, s[96:97]
	global_load_dwordx4 v[142:145], v173, s[86:87]
	global_load_dwordx4 v[194:197], v175, s[98:99]
	s_mov_b32 s30, 0x1f0000
	v_add_u32_e32 v174, s31, v168
	v_add_u32_e32 v164, s39, v169
	s_add_u32 s80, s42, s30
	s_addc_u32 s81, s43, 0
	s_add_u32 s86, s80, 0x7c000
	s_addc_u32 s87, s81, 0
	s_add_u32 s96, s46, s30
	s_addc_u32 s97, s47, 0
	s_add_u32 s98, s96, 0x7c000
	s_addc_u32 s99, s97, 0
	v_mov_b32_e32 v156, v165
	v_add_f32_e32 v157, 0x3f800000, v165
	v_add_f32_e32 v158, 0x40000000, v165
	v_add_f32_e32 v159, 0x40400000, v165
	v_add_f32_e32 v160, 0x41800000, v165
	v_add_f32_e32 v161, 0x41880000, v165
	v_add_f32_e32 v162, 0x41900000, v165
	v_add_f32_e32 v163, 0x41980000, v165
	v_add_f32_e32 v176, 0x42000000, v165
	v_add_f32_e32 v177, 0x42040000, v165
	v_add_f32_e32 v178, 0x42080000, v165
	v_add_f32_e32 v179, 0x420c0000, v165
	v_add_f32_e32 v180, 0x42400000, v165
	v_add_f32_e32 v181, 0x42440000, v165
	v_add_f32_e32 v182, 0x42480000, v165
	v_add_f32_e32 v183, 0x424c0000, v165
	v_fma_f32 v204, -v150, |v156|, v25
	v_fma_f32 v205, -v150, |v157|, v25
	v_fma_f32 v206, -v150, |v158|, v25
	v_fma_f32 v207, -v150, |v159|, v25
	v_fma_f32 v208, -v150, |v160|, v25
	v_fma_f32 v209, -v150, |v161|, v25
	v_fma_f32 v210, -v150, |v162|, v25
	v_fma_f32 v211, -v150, |v163|, v25
	v_fma_f32 v184, -v150, |v176|, v25
	v_fma_f32 v185, -v150, |v177|, v25
	v_fma_f32 v186, -v150, |v178|, v25
	v_fma_f32 v187, -v150, |v179|, v25
	v_fma_f32 v188, -v150, |v180|, v25
	v_fma_f32 v189, -v150, |v181|, v25
	v_fma_f32 v190, -v150, |v182|, v25
	v_fma_f32 v191, -v150, |v183|, v25
	v_fma_f32 v156, -v150, |v156|, v24
	v_fma_f32 v157, -v150, |v157|, v24
	v_fma_f32 v158, -v150, |v158|, v24
	v_fma_f32 v159, -v150, |v159|, v24
	v_fma_f32 v160, -v150, |v160|, v24
	v_fma_f32 v161, -v150, |v161|, v24
	v_fma_f32 v162, -v150, |v162|, v24
	v_fma_f32 v163, -v150, |v163|, v24
	v_fma_f32 v176, -v150, |v176|, v24
	v_fma_f32 v177, -v150, |v177|, v24
	v_fma_f32 v178, -v150, |v178|, v24
	v_fma_f32 v179, -v150, |v179|, v24
	v_fma_f32 v180, -v150, |v180|, v24
	v_fma_f32 v181, -v150, |v181|, v24
	v_fma_f32 v182, -v150, |v182|, v24
	v_fma_f32 v183, -v150, |v183|, v24

.Ld_nr_A0_1:
	v_exp_f32_e32 v104, v104
	v_exp_f32_e32 v105, v105
	v_exp_f32_e32 v106, v106
	v_exp_f32_e32 v107, v107
	v_exp_f32_e32 v108, v108
	v_exp_f32_e32 v109, v109
	v_exp_f32_e32 v110, v110
	v_exp_f32_e32 v111, v111
	v_exp_f32_e32 v112, v112
	v_exp_f32_e32 v113, v113
	v_exp_f32_e32 v114, v114
	v_exp_f32_e32 v115, v115
	v_exp_f32_e32 v116, v116
	v_exp_f32_e32 v117, v117
	v_exp_f32_e32 v118, v118
	v_exp_f32_e32 v119, v119
	s_nop 0
	v_add_f32_e32 v26, v104, v105
	v_add_f32_e32 v26, v26, v106
	v_add_f32_e32 v26, v26, v107
	v_add_f32_e32 v26, v26, v108
	v_add_f32_e32 v26, v26, v109
	v_add_f32_e32 v26, v26, v110
	v_add_f32_e32 v26, v26, v111
	v_add_f32_e32 v26, v26, v112
	v_add_f32_e32 v26, v26, v113
	v_add_f32_e32 v26, v26, v114
	v_add_f32_e32 v26, v26, v115
	v_add_f32_e32 v26, v26, v116
	v_add_f32_e32 v26, v26, v117
	v_add_f32_e32 v26, v26, v118
	v_add_f32_e32 v26, v26, v119
	v_add_f32_e32 v151, v151, v26
	v_cvt_pk_bf16_f32 v128, v104, v105
	v_cvt_pk_bf16_f32 v129, v106, v107
	v_cvt_pk_bf16_f32 v130, v108, v109
	v_cvt_pk_bf16_f32 v131, v110, v111
	v_cvt_pk_bf16_f32 v152, v112, v113
	v_cvt_pk_bf16_f32 v153, v114, v115
	v_cvt_pk_bf16_f32 v154, v116, v117
	v_cvt_pk_bf16_f32 v155, v118, v119
	v_add_f32_e32 v165, 0x42800000, v165
	v_mov_b32_e32 v156, v165
	v_add_f32_e32 v157, 0x3f800000, v165
	v_add_f32_e32 v158, 0x40000000, v165
	v_add_f32_e32 v159, 0x40400000, v165
	v_add_f32_e32 v160, 0x41800000, v165
	v_add_f32_e32 v161, 0x41880000, v165
	v_add_f32_e32 v162, 0x41900000, v165
	v_add_f32_e32 v163, 0x41980000, v165
	v_add_f32_e32 v176, 0x42000000, v165
	v_add_f32_e32 v177, 0x42040000, v165
	v_add_f32_e32 v178, 0x42080000, v165
	v_add_f32_e32 v179, 0x420c0000, v165
	v_add_f32_e32 v180, 0x42400000, v165
	v_add_f32_e32 v181, 0x42440000, v165
	v_add_f32_e32 v182, 0x42480000, v165
	v_add_f32_e32 v183, 0x424c0000, v165
	v_fma_f32 v204, -v150, |v156|, v25
	v_fma_f32 v205, -v150, |v157|, v25
	v_fma_f32 v206, -v150, |v158|, v25
	v_fma_f32 v207, -v150, |v159|, v25
	v_fma_f32 v208, -v150, |v160|, v25
	v_fma_f32 v209, -v150, |v161|, v25
	v_fma_f32 v210, -v150, |v162|, v25
	v_fma_f32 v211, -v150, |v163|, v25
	v_fma_f32 v184, -v150, |v176|, v25
	v_fma_f32 v185, -v150, |v177|, v25
	v_fma_f32 v186, -v150, |v178|, v25
	v_fma_f32 v187, -v150, |v179|, v25
	v_fma_f32 v188, -v150, |v180|, v25
	v_fma_f32 v189, -v150, |v181|, v25
	v_fma_f32 v190, -v150, |v182|, v25
	v_fma_f32 v191, -v150, |v183|, v25
	v_fma_f32 v156, -v150, |v156|, v24
	v_fma_f32 v157, -v150, |v157|, v24
	v_fma_f32 v158, -v150, |v158|, v24
	v_fma_f32 v159, -v150, |v159|, v24
	v_fma_f32 v160, -v150, |v160|, v24
	v_fma_f32 v161, -v150, |v161|, v24
	v_fma_f32 v162, -v150, |v162|, v24
	v_fma_f32 v163, -v150, |v163|, v24
	v_fma_f32 v176, -v150, |v176|, v24
	v_fma_f32 v177, -v150, |v177|, v24
	v_fma_f32 v178, -v150, |v178|, v24
	v_fma_f32 v179, -v150, |v179|, v24
	v_fma_f32 v180, -v150, |v180|, v24
	v_fma_f32 v181, -v150, |v181|, v24
	v_fma_f32 v182, -v150, |v182|, v24
	v_fma_f32 v183, -v150, |v183|, v24
	s_waitcnt vmcnt(4)
	ds_write_b128 v169, v[138:141] offset:18432
	ds_write_b128 v169, v[142:145] offset:27648
	ds_write_b128 v164, v[146:149] offset:36864
	ds_write_b128 v164, v[194:197] offset:46080
	s_mov_b32 s31, s38
	s_mov_b32 s38, s39
	s_add_i32 s39, s39, 0x4800
	s_cmp_lg_u32 s39, 0xd800
	s_cselect_b32 s39, s39, 0
	s_mov_b32 s66, 0x42800000
	s_add_i32 s5, s5, 1
	s_add_i32 s8, s5, 2
	s_min_u32 s8, s8, 63
	s_mul_i32 s30, s8, 0xf8000
	v_add_u32_e32 v174, s31, v168
	v_add_u32_e32 v164, s39, v169
	s_add_u32 s80, s42, s30
	s_addc_u32 s81, s43, 0
	s_add_u32 s86, s80, 0x7c000
	s_addc_u32 s87, s81, 0
	s_add_u32 s96, s46, s30
	s_addc_u32 s97, s47, 0
	s_add_u32 s98, s96, 0x7c000
	s_addc_u32 s99, s97, 0
	s_waitcnt lgkmcnt(0)
	s_barrier
	global_load_dwordx4 v[138:141], v173, s[80:81]
	global_load_dwordx4 v[146:149], v175, s[96:97]
	global_load_dwordx4 v[142:145], v173, s[86:87]
	global_load_dwordx4 v[194:197], v175, s[98:99]
	ds_read_b64_tr_b16 v[228:229], v174 offset:36864
	ds_read_b64_tr_b16 v[230:231], v174 offset:41472
	ds_read_b64_tr_b16 v[232:233], v174 offset:36896
	ds_read_b64_tr_b16 v[234:235], v174 offset:41504
	ds_read_b64_tr_b16 v[236:237], v174 offset:36928
	ds_read_b64_tr_b16 v[238:239], v174 offset:41536
	ds_read_b64_tr_b16 v[240:241], v174 offset:36960
	ds_read_b64_tr_b16 v[242:243], v174 offset:41568
	ds_read_b64_tr_b16 v[244:245], v174 offset:36992
	ds_read_b64_tr_b16 v[246:247], v174 offset:41600
	s_waitcnt lgkmcnt(8)
	v_mfma_f32_16x16x32_bf16 v[28:31], v[228:231], v[120:123], v[28:31]
	v_mfma_f32_16x16x32_bf16 v[36:39], v[228:231], v[128:131], v[36:39]
	ds_read_b64_tr_b16 v[248:249], v174 offset:37024
	ds_read_b64_tr_b16 v[250:251], v174 offset:41632
	s_waitcnt lgkmcnt(8)
	v_mfma_f32_16x16x32_bf16 v[32:35], v[232:235], v[120:123], v[32:35]
	v_mfma_f32_16x16x32_bf16 v[44:47], v[232:235], v[128:131], v[44:47]
	ds_read_b64_tr_b16 v[228:229], v174 offset:37056
	ds_read_b64_tr_b16 v[230:231], v174 offset:41664
	s_waitcnt lgkmcnt(8)
	v_mfma_f32_16x16x32_bf16 v[40:43], v[236:239], v[120:123], v[40:43]
	v_mfma_f32_16x16x32_bf16 v[48:51], v[236:239], v[128:131], v[48:51]
	ds_read_b64_tr_b16 v[232:233], v174 offset:37088
	ds_read_b64_tr_b16 v[234:235], v174 offset:41696
	s_waitcnt lgkmcnt(8)
	v_mfma_f32_16x16x32_bf16 v[52:55], v[240:243], v[120:123], v[52:55]
	v_mfma_f32_16x16x32_bf16 v[60:63], v[240:243], v[128:131], v[60:63]
	ds_read_b64_tr_b16 v[236:237], v174 offset:46080
	ds_read_b64_tr_b16 v[238:239], v174 offset:50688
	s_waitcnt lgkmcnt(8)
	v_mfma_f32_16x16x32_bf16 v[56:59], v[244:247], v[120:123], v[56:59]
	v_mfma_f32_16x16x32_bf16 v[68:71], v[244:247], v[128:131], v[68:71]
	ds_read_b64_tr_b16 v[240:241], v174 offset:46112
	ds_read_b64_tr_b16 v[242:243], v174 offset:50720
	s_waitcnt lgkmcnt(8)
	v_mfma_f32_16x16x32_bf16 v[64:67], v[248:251], v[120:123], v[64:67]
	v_mfma_f32_16x16x32_bf16 v[76:79], v[248:251], v[128:131], v[76:79]
	ds_read_b64_tr_b16 v[244:245], v174 offset:46144
	ds_read_b64_tr_b16 v[246:247], v174 offset:50752
	s_waitcnt lgkmcnt(8)
	v_mfma_f32_16x16x32_bf16 v[72:75], v[228:231], v[120:123], v[72:75]
	v_mfma_f32_16x16x32_bf16 v[80:83], v[228:231], v[128:131], v[80:83]
	ds_read_b64_tr_b16 v[248:249], v174 offset:46176
	ds_read_b64_tr_b16 v[250:251], v174 offset:50784
	s_waitcnt lgkmcnt(8)
	v_mfma_f32_16x16x32_bf16 v[84:87], v[232:235], v[120:123], v[84:87]
	v_mfma_f32_16x16x32_bf16 v[20:23], v[232:235], v[128:131], v[20:23]
	ds_read_b64_tr_b16 v[228:229], v174 offset:46208
	ds_read_b64_tr_b16 v[230:231], v174 offset:50816
	s_waitcnt lgkmcnt(8)
	v_mfma_f32_16x16x32_bf16 v[28:31], v[236:239], v[124:127], v[28:31]
	v_mfma_f32_16x16x32_bf16 v[36:39], v[236:239], v[152:155], v[36:39]
	ds_read_b64_tr_b16 v[232:233], v174 offset:46240
	ds_read_b64_tr_b16 v[234:235], v174 offset:50848
	s_waitcnt lgkmcnt(8)
	v_mfma_f32_16x16x32_bf16 v[32:35], v[240:243], v[124:127], v[32:35]
	v_mfma_f32_16x16x32_bf16 v[44:47], v[240:243], v[152:155], v[44:47]
	ds_read_b64_tr_b16 v[236:237], v174 offset:46272
	ds_read_b64_tr_b16 v[238:239], v174 offset:50880
	s_waitcnt lgkmcnt(8)
	v_mfma_f32_16x16x32_bf16 v[40:43], v[244:247], v[124:127], v[40:43]
	v_mfma_f32_16x16x32_bf16 v[48:51], v[244:247], v[152:155], v[48:51]
	ds_read_b64_tr_b16 v[240:241], v174 offset:46304
	ds_read_b64_tr_b16 v[242:243], v174 offset:50912
	s_waitcnt lgkmcnt(8)
	v_mfma_f32_16x16x32_bf16 v[52:55], v[248:251], v[124:127], v[52:55]
	v_mfma_f32_16x16x32_bf16 v[60:63], v[248:251], v[152:155], v[60:63]
	ds_read_b128 v[244:247], v255 offset:18432
	s_waitcnt lgkmcnt(7)
	v_mfma_f32_16x16x32_bf16 v[56:59], v[228:231], v[124:127], v[56:59]
	v_mfma_f32_16x16x32_bf16 v[68:71], v[228:231], v[152:155], v[68:71]
	ds_read_b128 v[248:251], v255 offset:18496
	s_waitcnt lgkmcnt(6)
	v_mfma_f32_16x16x32_bf16 v[64:67], v[232:235], v[124:127], v[64:67]
	v_mfma_f32_16x16x32_bf16 v[76:79], v[232:235], v[152:155], v[76:79]
	ds_read_b128 v[228:231], v255 offset:23040
	s_waitcnt lgkmcnt(5)
	v_mfma_f32_16x16x32_bf16 v[72:75], v[236:239], v[124:127], v[72:75]
	v_mfma_f32_16x16x32_bf16 v[80:83], v[236:239], v[152:155], v[80:83]
	ds_read_b128 v[232:235], v255 offset:23104
	s_waitcnt lgkmcnt(4)
	v_mfma_f32_16x16x32_bf16 v[84:87], v[240:243], v[124:127], v[84:87]
	v_mfma_f32_16x16x32_bf16 v[20:23], v[240:243], v[152:155], v[20:23]
	ds_read_b128 v[236:239], v255 offset:27648
	s_waitcnt lgkmcnt(4)
	v_mfma_f32_16x16x32_bf16 v[88:91], v[244:247], v[4:7], v[156:159]
	ds_read_b128 v[240:243], v255 offset:27712
	s_waitcnt lgkmcnt(4)
	v_mfma_f32_16x16x32_bf16 v[88:91], v[248:251], v[8:11], v[88:91]
	ds_read_b128 v[244:247], v255 offset:32256
	s_waitcnt lgkmcnt(4)
	v_mfma_f32_16x16x32_bf16 v[92:95], v[228:231], v[4:7], v[160:163]
	ds_read_b128 v[248:251], v255 offset:32320
	s_waitcnt lgkmcnt(4)
	v_mfma_f32_16x16x32_bf16 v[92:95], v[232:235], v[8:11], v[92:95]
	ds_read_b128 v[228:231], v255 offset:18560
	s_waitcnt lgkmcnt(4)
	v_mfma_f32_16x16x32_bf16 v[96:99], v[236:239], v[4:7], v[176:179]
	ds_read_b128 v[232:235], v255 offset:18624
	s_waitcnt lgkmcnt(4)
	v_mfma_f32_16x16x32_bf16 v[96:99], v[240:243], v[8:11], v[96:99]
	ds_read_b128 v[236:239], v255 offset:23168
	s_waitcnt lgkmcnt(4)
	v_mfma_f32_16x16x32_bf16 v[100:103], v[244:247], v[4:7], v[180:183]
	ds_read_b128 v[240:243], v255 offset:23232
	s_waitcnt lgkmcnt(4)
	v_mfma_f32_16x16x32_bf16 v[100:103], v[248:251], v[8:11], v[100:103]
	ds_read_b128 v[244:247], v255 offset:27776
	s_waitcnt lgkmcnt(4)
	v_mfma_f32_16x16x32_bf16 v[104:107], v[228:231], v[12:15], v[204:207]
	ds_read_b128 v[248:251], v255 offset:27840
	s_waitcnt lgkmcnt(4)
	v_mfma_f32_16x16x32_bf16 v[104:107], v[232:235], v[16:19], v[104:107]
	ds_read_b128 v[228:231], v255 offset:32384
	s_waitcnt lgkmcnt(4)
	v_mfma_f32_16x16x32_bf16 v[108:111], v[236:239], v[12:15], v[208:211]
	ds_read_b128 v[232:235], v255 offset:32448
	s_waitcnt lgkmcnt(4)
	v_mfma_f32_16x16x32_bf16 v[108:111], v[240:243], v[16:19], v[108:111]
	s_waitcnt lgkmcnt(3)
	v_mfma_f32_16x16x32_bf16 v[112:115], v[244:247], v[12:15], v[184:187]
	s_waitcnt lgkmcnt(2)
	v_mfma_f32_16x16x32_bf16 v[112:115], v[248:251], v[16:19], v[112:115]
	s_waitcnt lgkmcnt(1)
	v_mfma_f32_16x16x32_bf16 v[116:119], v[228:231], v[12:15], v[188:191]
	s_waitcnt lgkmcnt(0)
	v_mfma_f32_16x16x32_bf16 v[116:119], v[232:235], v[16:19], v[116:119]
	v_max3_f32 v26, v88, v89, v90
	v_max3_f32 v26, v26, v91, v92
	v_max3_f32 v26, v26, v93, v94
	v_max3_f32 v26, v26, v95, v96
	v_max3_f32 v26, v26, v97, v98
	v_max3_f32 v26, v26, v99, v100
	v_max3_f32 v26, v26, v101, v102
	v_max_f32_e32 v26, v26, v103
	v_cmp_lt_f32_e32 vcc, s66, v26
	s_cbranch_vccz .Ld_nr_A1_0
	v_mov_b32_e32 v27, v26
	s_nop 1
	v_permlane16_swap_b32_e32 v26, v27
	v_max_f32_e32 v26, v26, v27
	v_mov_b32_e32 v27, v26
	s_nop 1
	v_permlane32_swap_b32_e32 v26, v27
	v_max_f32_e32 v26, v26, v27
	v_cmp_lt_f32_e32 vcc, s66, v26
	s_nop 1
	v_cndmask_b32_e32 v3, 0, v26, vcc
	v_sub_f32_e32 v2, 0, v3
	v_min_f32_e32 v2, 0, v2
	v_exp_f32_e32 v2, v2
	v_sub_f32_e32 v24, v24, v3
	v_mul_f32_e32 v0, v0, v2
	v_mul_f32_e32 v28, v28, v2
	v_mul_f32_e32 v29, v29, v2
	v_mul_f32_e32 v30, v30, v2
	v_mul_f32_e32 v31, v31, v2
	v_mul_f32_e32 v32, v32, v2
	v_mul_f32_e32 v33, v33, v2
	v_mul_f32_e32 v34, v34, v2
	v_mul_f32_e32 v35, v35, v2
	v_mul_f32_e32 v40, v40, v2
	v_mul_f32_e32 v41, v41, v2
	v_mul_f32_e32 v42, v42, v2
	v_mul_f32_e32 v43, v43, v2
	v_mul_f32_e32 v52, v52, v2
	v_mul_f32_e32 v53, v53, v2
	v_mul_f32_e32 v54, v54, v2
	v_mul_f32_e32 v55, v55, v2
	v_mul_f32_e32 v56, v56, v2
	v_mul_f32_e32 v57, v57, v2
	v_mul_f32_e32 v58, v58, v2
	v_mul_f32_e32 v59, v59, v2
	v_mul_f32_e32 v64, v64, v2
	v_mul_f32_e32 v65, v65, v2
	v_mul_f32_e32 v66, v66, v2
	v_mul_f32_e32 v67, v67, v2
	v_mul_f32_e32 v72, v72, v2
	v_mul_f32_e32 v73, v73, v2
	v_mul_f32_e32 v74, v74, v2
	v_mul_f32_e32 v75, v75, v2
	v_mul_f32_e32 v84, v84, v2
	v_mul_f32_e32 v85, v85, v2
	v_mul_f32_e32 v86, v86, v2
	v_mul_f32_e32 v87, v87, v2
	v_sub_f32_e32 v88, v88, v3
	v_sub_f32_e32 v89, v89, v3
	v_sub_f32_e32 v90, v90, v3
	v_sub_f32_e32 v91, v91, v3
	v_sub_f32_e32 v92, v92, v3
	v_sub_f32_e32 v93, v93, v3
	v_sub_f32_e32 v94, v94, v3
	v_sub_f32_e32 v95, v95, v3
	v_sub_f32_e32 v96, v96, v3
	v_sub_f32_e32 v97, v97, v3
	v_sub_f32_e32 v98, v98, v3
	v_sub_f32_e32 v99, v99, v3
	v_sub_f32_e32 v100, v100, v3
	v_sub_f32_e32 v101, v101, v3
	v_sub_f32_e32 v102, v102, v3
	v_sub_f32_e32 v103, v103, v3

.Ld_nr_A1_1:
	v_exp_f32_e32 v104, v104
	v_exp_f32_e32 v105, v105
	v_exp_f32_e32 v106, v106
	v_exp_f32_e32 v107, v107
	v_exp_f32_e32 v108, v108
	v_exp_f32_e32 v109, v109
	v_exp_f32_e32 v110, v110
	v_exp_f32_e32 v111, v111
	v_exp_f32_e32 v112, v112
	v_exp_f32_e32 v113, v113
	v_exp_f32_e32 v114, v114
	v_exp_f32_e32 v115, v115
	v_exp_f32_e32 v116, v116
	v_exp_f32_e32 v117, v117
	v_exp_f32_e32 v118, v118
	v_exp_f32_e32 v119, v119
	s_nop 0
	v_add_f32_e32 v26, v104, v105
	v_add_f32_e32 v26, v26, v106
	v_add_f32_e32 v26, v26, v107
	v_add_f32_e32 v26, v26, v108
	v_add_f32_e32 v26, v26, v109
	v_add_f32_e32 v26, v26, v110
	v_add_f32_e32 v26, v26, v111
	v_add_f32_e32 v26, v26, v112
	v_add_f32_e32 v26, v26, v113
	v_add_f32_e32 v26, v26, v114
	v_add_f32_e32 v26, v26, v115
	v_add_f32_e32 v26, v26, v116
	v_add_f32_e32 v26, v26, v117
	v_add_f32_e32 v26, v26, v118
	v_add_f32_e32 v26, v26, v119
	v_add_f32_e32 v151, v151, v26
	v_cvt_pk_bf16_f32 v128, v104, v105
	v_cvt_pk_bf16_f32 v129, v106, v107
	v_cvt_pk_bf16_f32 v130, v108, v109
	v_cvt_pk_bf16_f32 v131, v110, v111
	v_cvt_pk_bf16_f32 v152, v112, v113
	v_cvt_pk_bf16_f32 v153, v114, v115
	v_cvt_pk_bf16_f32 v154, v116, v117
	v_cvt_pk_bf16_f32 v155, v118, v119
	v_add_f32_e32 v165, 0x42800000, v165
	v_mov_b32_e32 v156, v165
	v_add_f32_e32 v157, 0x3f800000, v165
	v_add_f32_e32 v158, 0x40000000, v165
	v_add_f32_e32 v159, 0x40400000, v165
	v_add_f32_e32 v160, 0x41800000, v165
	v_add_f32_e32 v161, 0x41880000, v165
	v_add_f32_e32 v162, 0x41900000, v165
	v_add_f32_e32 v163, 0x41980000, v165
	v_add_f32_e32 v176, 0x42000000, v165
	v_add_f32_e32 v177, 0x42040000, v165
	v_add_f32_e32 v178, 0x42080000, v165
	v_add_f32_e32 v179, 0x420c0000, v165
	v_add_f32_e32 v180, 0x42400000, v165
	v_add_f32_e32 v181, 0x42440000, v165
	v_add_f32_e32 v182, 0x42480000, v165
	v_add_f32_e32 v183, 0x424c0000, v165
	v_fma_f32 v204, -v150, |v156|, v25
	v_fma_f32 v205, -v150, |v157|, v25
	v_fma_f32 v206, -v150, |v158|, v25
	v_fma_f32 v207, -v150, |v159|, v25
	v_fma_f32 v208, -v150, |v160|, v25
	v_fma_f32 v209, -v150, |v161|, v25
	v_fma_f32 v210, -v150, |v162|, v25
	v_fma_f32 v211, -v150, |v163|, v25
	v_fma_f32 v184, -v150, |v176|, v25
	v_fma_f32 v185, -v150, |v177|, v25
	v_fma_f32 v186, -v150, |v178|, v25
	v_fma_f32 v187, -v150, |v179|, v25
	v_fma_f32 v188, -v150, |v180|, v25
	v_fma_f32 v189, -v150, |v181|, v25
	v_fma_f32 v190, -v150, |v182|, v25
	v_fma_f32 v191, -v150, |v183|, v25
	v_fma_f32 v156, -v150, |v156|, v24
	v_fma_f32 v157, -v150, |v157|, v24
	v_fma_f32 v158, -v150, |v158|, v24
	v_fma_f32 v159, -v150, |v159|, v24
	v_fma_f32 v160, -v150, |v160|, v24
	v_fma_f32 v161, -v150, |v161|, v24
	v_fma_f32 v162, -v150, |v162|, v24
	v_fma_f32 v163, -v150, |v163|, v24
	v_fma_f32 v176, -v150, |v176|, v24
	v_fma_f32 v177, -v150, |v177|, v24
	v_fma_f32 v178, -v150, |v178|, v24
	v_fma_f32 v179, -v150, |v179|, v24
	v_fma_f32 v180, -v150, |v180|, v24
	v_fma_f32 v181, -v150, |v181|, v24
	v_fma_f32 v182, -v150, |v182|, v24
	v_fma_f32 v183, -v150, |v183|, v24
	s_waitcnt vmcnt(4)
	ds_write_b128 v169, v[212:215] offset:0
	ds_write_b128 v169, v[216:219] offset:9216
	ds_write_b128 v164, v[220:223] offset:36864
	ds_write_b128 v164, v[224:227] offset:46080
	s_mov_b32 s31, s38
	s_mov_b32 s38, s39
	s_add_i32 s39, s39, 0x4800
	s_cmp_lg_u32 s39, 0xd800
	s_cselect_b32 s39, s39, 0
	s_mov_b32 s66, 0x42800000
	s_add_i32 s5, s5, 1
	s_add_i32 s8, s5, 2
	s_min_u32 s8, s8, 63
	s_mul_i32 s30, s8, 0xf8000
	v_add_u32_e32 v174, s31, v168
	v_add_u32_e32 v164, s39, v169
	s_add_u32 s80, s42, s30
	s_addc_u32 s81, s43, 0
	s_add_u32 s86, s80, 0x7c000
	s_addc_u32 s87, s81, 0
	s_add_u32 s96, s46, s30
	s_addc_u32 s97, s47, 0
	s_add_u32 s98, s96, 0x7c000
	s_addc_u32 s99, s97, 0
	s_waitcnt lgkmcnt(0)
	s_barrier
	s_cmp_lt_u32 s5, 64
	s_cbranch_scc1 .Ld_loopA
	v_add_u32_e32 v174, s31, v168
	ds_read_b64_tr_b16 v[228:229], v174 offset:36864
	ds_read_b64_tr_b16 v[230:231], v174 offset:41472
	ds_read_b64_tr_b16 v[232:233], v174 offset:36896
	ds_read_b64_tr_b16 v[234:235], v174 offset:41504
	ds_read_b64_tr_b16 v[236:237], v174 offset:36928
	ds_read_b64_tr_b16 v[238:239], v174 offset:41536
	ds_read_b64_tr_b16 v[240:241], v174 offset:36960
	ds_read_b64_tr_b16 v[242:243], v174 offset:41568
	ds_read_b64_tr_b16 v[244:245], v174 offset:36992
	ds_read_b64_tr_b16 v[246:247], v174 offset:41600
	s_waitcnt lgkmcnt(8)
	v_mfma_f32_16x16x32_bf16 v[28:31], v[228:231], v[120:123], v[28:31]
	v_mfma_f32_16x16x32_bf16 v[36:39], v[228:231], v[128:131], v[36:39]
	ds_read_b64_tr_b16 v[248:249], v174 offset:37024
	ds_read_b64_tr_b16 v[250:251], v174 offset:41632
	s_waitcnt lgkmcnt(8)
	v_mfma_f32_16x16x32_bf16 v[32:35], v[232:235], v[120:123], v[32:35]
	v_mfma_f32_16x16x32_bf16 v[44:47], v[232:235], v[128:131], v[44:47]
	ds_read_b64_tr_b16 v[228:229], v174 offset:37056
	ds_read_b64_tr_b16 v[230:231], v174 offset:41664
	s_waitcnt lgkmcnt(8)
	v_mfma_f32_16x16x32_bf16 v[40:43], v[236:239], v[120:123], v[40:43]
	v_mfma_f32_16x16x32_bf16 v[48:51], v[236:239], v[128:131], v[48:51]
	ds_read_b64_tr_b16 v[232:233], v174 offset:37088
	ds_read_b64_tr_b16 v[234:235], v174 offset:41696
	s_waitcnt lgkmcnt(8)
	v_mfma_f32_16x16x32_bf16 v[52:55], v[240:243], v[120:123], v[52:55]
	v_mfma_f32_16x16x32_bf16 v[60:63], v[240:243], v[128:131], v[60:63]
	ds_read_b64_tr_b16 v[236:237], v174 offset:46080
	ds_read_b64_tr_b16 v[238:239], v174 offset:50688
	s_waitcnt lgkmcnt(8)
	v_mfma_f32_16x16x32_bf16 v[56:59], v[244:247], v[120:123], v[56:59]
	v_mfma_f32_16x16x32_bf16 v[68:71], v[244:247], v[128:131], v[68:71]
	ds_read_b64_tr_b16 v[240:241], v174 offset:46112
	ds_read_b64_tr_b16 v[242:243], v174 offset:50720
	s_waitcnt lgkmcnt(8)
	v_mfma_f32_16x16x32_bf16 v[64:67], v[248:251], v[120:123], v[64:67]
	v_mfma_f32_16x16x32_bf16 v[76:79], v[248:251], v[128:131], v[76:79]
	ds_read_b64_tr_b16 v[244:245], v174 offset:46144
	ds_read_b64_tr_b16 v[246:247], v174 offset:50752
	s_waitcnt lgkmcnt(8)
	v_mfma_f32_16x16x32_bf16 v[72:75], v[228:231], v[120:123], v[72:75]
	v_mfma_f32_16x16x32_bf16 v[80:83], v[228:231], v[128:131], v[80:83]
	ds_read_b64_tr_b16 v[248:249], v174 offset:46176
	ds_read_b64_tr_b16 v[250:251], v174 offset:50784
	s_waitcnt lgkmcnt(8)
	v_mfma_f32_16x16x32_bf16 v[84:87], v[232:235], v[120:123], v[84:87]
	v_mfma_f32_16x16x32_bf16 v[20:23], v[232:235], v[128:131], v[20:23]
	ds_read_b64_tr_b16 v[228:229], v174 offset:46208
	ds_read_b64_tr_b16 v[230:231], v174 offset:50816
	s_waitcnt lgkmcnt(8)
	v_mfma_f32_16x16x32_bf16 v[28:31], v[236:239], v[124:127], v[28:31]
	v_mfma_f32_16x16x32_bf16 v[36:39], v[236:239], v[152:155], v[36:39]
	ds_read_b64_tr_b16 v[232:233], v174 offset:46240
	ds_read_b64_tr_b16 v[234:235], v174 offset:50848
	s_waitcnt lgkmcnt(8)
	v_mfma_f32_16x16x32_bf16 v[32:35], v[240:243], v[124:127], v[32:35]
	v_mfma_f32_16x16x32_bf16 v[44:47], v[240:243], v[152:155], v[44:47]
	ds_read_b64_tr_b16 v[236:237], v174 offset:46272
	ds_read_b64_tr_b16 v[238:239], v174 offset:50880
	s_waitcnt lgkmcnt(8)
	v_mfma_f32_16x16x32_bf16 v[40:43], v[244:247], v[124:127], v[40:43]
	v_mfma_f32_16x16x32_bf16 v[48:51], v[244:247], v[152:155], v[48:51]
	ds_read_b64_tr_b16 v[240:241], v174 offset:46304
	ds_read_b64_tr_b16 v[242:243], v174 offset:50912
	s_waitcnt lgkmcnt(8)
	v_mfma_f32_16x16x32_bf16 v[52:55], v[248:251], v[124:127], v[52:55]
	v_mfma_f32_16x16x32_bf16 v[60:63], v[248:251], v[152:155], v[60:63]
	s_waitcnt lgkmcnt(6)
	v_mfma_f32_16x16x32_bf16 v[56:59], v[228:231], v[124:127], v[56:59]
	v_mfma_f32_16x16x32_bf16 v[68:71], v[228:231], v[152:155], v[68:71]
	s_waitcnt lgkmcnt(4)
	v_mfma_f32_16x16x32_bf16 v[64:67], v[232:235], v[124:127], v[64:67]
	v_mfma_f32_16x16x32_bf16 v[76:79], v[232:235], v[152:155], v[76:79]
	s_waitcnt lgkmcnt(2)
	v_mfma_f32_16x16x32_bf16 v[72:75], v[236:239], v[124:127], v[72:75]
	v_mfma_f32_16x16x32_bf16 v[80:83], v[236:239], v[152:155], v[80:83]
	s_waitcnt lgkmcnt(0)
	v_mfma_f32_16x16x32_bf16 v[84:87], v[240:243], v[124:127], v[84:87]
	v_mfma_f32_16x16x32_bf16 v[20:23], v[240:243], v[152:155], v[20:23]
	s_waitcnt vmcnt(0)
	v_mov_b32_e32 v138, 0xa00
	v_mov_b32_e32 v139, 0x0
	v_mov_b32_e32 v140, 0x9ff
	v_mov_b32_e32 v141, 0x0
	v_mov_b32_e32 v142, 0x200
	v_mov_b32_e32 v143, 0x0
	v_mov_b32_e32 v144, 0x1ff
	v_mov_b32_e32 v145, 0x0
	v_mov_b32_e32 v146, 0xb00
	v_mov_b32_e32 v147, 0x0
	v_mov_b32_e32 v148, 0xaff
	v_mov_b32_e32 v149, 0x0
	v_mov_b32_e32 v194, 0x358637bd
	v_mov_b32_e32 v195, 0x2000
	v_mov_b32_e32 v196, 0x3e38aa3b
	v_mov_b32_e32 v197, 0x41b17218
